# merge phase: non-temporal hint on the thread-private gate / running-Y scratch loads and stores
# baseline (speedup 1.0000x reference)
.LBB0_1261:
	s_and_b32 s70, s65, -4
	v_mul_f32_e32 v122, 0xbfb8aa3b, v122
	v_mov_b32_e32 v150, v5
	v_mov_b32_e32 v151, v139
	s_cmp_eq_u32 s70, 4
	v_mul_f32_e32 v126, 0xbfb8aa3b, v126
	v_exp_f32_e32 v122, v122
	v_mul_f32_e32 v123, 0xbfb8aa3b, v123
	s_cselect_b32 s70, 0x4512000, s93
	s_cmp_gt_u32 s65, 3
	v_exp_f32_e32 v152, v126
	v_exp_f32_e32 v123, v123
	s_cselect_b32 s70, s70, 0x8d12000
	v_lshlrev_b32_e32 v151, 4, v151
	s_add_u32 s70, s26, s70
	v_add3_u32 v150, s51, v150, v151
	s_addc_u32 s71, s27, 0
	v_ashrrev_i32_e32 v151, 31, v150
	v_mul_f32_e32 v126, 0xbfb8aa3b, v127
	v_add_f32_e32 v122, 1.0, v122
	v_exp_f32_e32 v153, v126
	v_lshl_add_u64 v[126:127], v[150:151], 4, s[70:71]
	v_add_f32_e32 v150, 1.0, v152
	v_rcp_f32_e32 v152, v122
	v_add_f32_e32 v122, 1.0, v123
	v_mul_f32_e32 v123, 0xbfb8aa3b, v124
	v_mul_f32_e32 v128, 0xbfb8aa3b, v128
	v_mul_f32_e32 v129, 0xbfb8aa3b, v129
	v_exp_f32_e32 v123, v123
	v_mul_f32_e32 v124, 0xbfb8aa3b, v125
	v_exp_f32_e32 v128, v128
	v_exp_f32_e32 v129, v129
	v_exp_f32_e32 v124, v124
	v_rcp_f32_e32 v125, v122
	v_add_f32_e32 v122, 1.0, v123
	s_lshl_b32 s65, s65, 4
	v_add_f32_e32 v151, 1.0, v153
	v_add_f32_e32 v128, 1.0, v128
	v_add_f32_e32 v129, 1.0, v129
	v_rcp_f32_e32 v153, v122
	v_add_f32_e32 v122, 1.0, v124
	v_mul_f32_e32 v114, 0xbfb8aa3b, v114
	s_and_b32 s65, s65, 48
	v_rcp_f32_e32 v150, v150
	v_rcp_f32_e32 v151, v151
	v_rcp_f32_e32 v128, v128
	v_rcp_f32_e32 v129, v129
	v_rcp_f32_e32 v154, v122
	v_exp_f32_e32 v114, v114
	v_mul_f32_e32 v115, 0xbfb8aa3b, v115
	s_or_b32 s70, s65, s56
	v_exp_f32_e32 v115, v115
	s_ashr_i32 s71, s70, 31
	s_lshl_b64 s[72:73], s[70:71], 13
	v_cvt_pk_bf16_f32 v122, v150, v151
	v_cvt_pk_bf16_f32 v123, v128, v129
	v_cvt_pk_bf16_f32 v124, v152, v125
	v_cvt_pk_bf16_f32 v125, v153, v154
	v_lshl_add_u64 v[128:129], v[126:127], 0, s[72:73]
	v_add_f32_e32 v114, 1.0, v114
	global_store_dwordx4 v[128:129], v[122:125], off nt
	v_mul_f32_e32 v118, 0xbfb8aa3b, v118
	v_mul_f32_e32 v119, 0xbfb8aa3b, v119
	v_rcp_f32_e32 v122, v114
	v_add_f32_e32 v114, 1.0, v115
	v_mul_f32_e32 v115, 0xbfb8aa3b, v116
	v_mul_f32_e32 v120, 0xbfb8aa3b, v120
	v_mul_f32_e32 v121, 0xbfb8aa3b, v121
	v_exp_f32_e32 v115, v115
	v_mul_f32_e32 v116, 0xbfb8aa3b, v117
	v_exp_f32_e32 v118, v118
	v_exp_f32_e32 v119, v119
	v_exp_f32_e32 v120, v120
	v_exp_f32_e32 v121, v121
	v_exp_f32_e32 v116, v116
	v_rcp_f32_e32 v117, v114
	v_add_f32_e32 v114, 1.0, v115
	v_add_f32_e32 v118, 1.0, v118
	v_add_f32_e32 v119, 1.0, v119
	v_add_f32_e32 v120, 1.0, v120
	v_add_f32_e32 v121, 1.0, v121
	v_rcp_f32_e32 v123, v114
	v_add_f32_e32 v114, 1.0, v116
	v_mul_f32_e32 v106, 0xbfb8aa3b, v106
	v_rcp_f32_e32 v118, v118
	v_rcp_f32_e32 v119, v119
	v_rcp_f32_e32 v120, v120
	v_rcp_f32_e32 v121, v121
	v_rcp_f32_e32 v124, v114
	v_exp_f32_e32 v106, v106
	v_mul_f32_e32 v107, 0xbfb8aa3b, v107
	s_or_b32 s72, s70, 1
	v_exp_f32_e32 v107, v107
	s_ashr_i32 s73, s72, 31
	s_lshl_b64 s[72:73], s[72:73], 13
	v_cvt_pk_bf16_f32 v114, v118, v119
	v_cvt_pk_bf16_f32 v115, v120, v121
	v_cvt_pk_bf16_f32 v116, v122, v117
	v_cvt_pk_bf16_f32 v117, v123, v124
	v_lshl_add_u64 v[118:119], v[126:127], 0, s[72:73]
	v_add_f32_e32 v106, 1.0, v106
	global_store_dwordx4 v[118:119], v[114:117], off nt
	v_mul_f32_e32 v110, 0xbfb8aa3b, v110
	v_mul_f32_e32 v111, 0xbfb8aa3b, v111
	v_rcp_f32_e32 v114, v106
	v_add_f32_e32 v106, 1.0, v107
	v_mul_f32_e32 v107, 0xbfb8aa3b, v108
	v_mul_f32_e32 v112, 0xbfb8aa3b, v112
	v_mul_f32_e32 v113, 0xbfb8aa3b, v113
	v_exp_f32_e32 v107, v107
	v_mul_f32_e32 v108, 0xbfb8aa3b, v109
	v_exp_f32_e32 v110, v110
	v_exp_f32_e32 v111, v111
	v_exp_f32_e32 v112, v112
	v_exp_f32_e32 v113, v113
	v_exp_f32_e32 v108, v108
	v_rcp_f32_e32 v109, v106
	v_add_f32_e32 v106, 1.0, v107
	v_add_f32_e32 v110, 1.0, v110
	v_add_f32_e32 v111, 1.0, v111
	v_add_f32_e32 v112, 1.0, v112
	v_add_f32_e32 v113, 1.0, v113
	v_rcp_f32_e32 v115, v106
	v_add_f32_e32 v106, 1.0, v108
	v_mul_f32_e32 v98, 0xbfb8aa3b, v98
	v_rcp_f32_e32 v110, v110
	v_rcp_f32_e32 v111, v111
	v_rcp_f32_e32 v112, v112
	v_rcp_f32_e32 v113, v113
	v_rcp_f32_e32 v116, v106
	v_exp_f32_e32 v98, v98
	v_mul_f32_e32 v99, 0xbfb8aa3b, v99
	s_or_b32 s72, s70, 2
	v_exp_f32_e32 v99, v99
	s_ashr_i32 s73, s72, 31
	s_lshl_b64 s[72:73], s[72:73], 13
	v_cvt_pk_bf16_f32 v106, v110, v111
	v_cvt_pk_bf16_f32 v107, v112, v113
	v_cvt_pk_bf16_f32 v108, v114, v109
	v_cvt_pk_bf16_f32 v109, v115, v116
	v_lshl_add_u64 v[110:111], v[126:127], 0, s[72:73]
	v_add_f32_e32 v98, 1.0, v98
	global_store_dwordx4 v[110:111], v[106:109], off nt
	v_mul_f32_e32 v102, 0xbfb8aa3b, v102
	v_mul_f32_e32 v103, 0xbfb8aa3b, v103
	v_rcp_f32_e32 v106, v98
	v_add_f32_e32 v98, 1.0, v99
	v_mul_f32_e32 v99, 0xbfb8aa3b, v100
	v_mul_f32_e32 v104, 0xbfb8aa3b, v104
	v_mul_f32_e32 v105, 0xbfb8aa3b, v105
	v_exp_f32_e32 v99, v99
	v_mul_f32_e32 v100, 0xbfb8aa3b, v101
	v_exp_f32_e32 v102, v102
	v_exp_f32_e32 v103, v103
	v_exp_f32_e32 v104, v104
	v_exp_f32_e32 v105, v105
	v_exp_f32_e32 v100, v100
	v_rcp_f32_e32 v101, v98
	v_add_f32_e32 v98, 1.0, v99
	v_add_f32_e32 v102, 1.0, v102
	v_add_f32_e32 v103, 1.0, v103
	v_add_f32_e32 v104, 1.0, v104
	v_add_f32_e32 v105, 1.0, v105
	v_rcp_f32_e32 v107, v98
	v_add_f32_e32 v98, 1.0, v100
	v_mul_f32_e32 v90, 0xbfb8aa3b, v90
	v_rcp_f32_e32 v102, v102
	v_rcp_f32_e32 v103, v103
	v_rcp_f32_e32 v104, v104
	v_rcp_f32_e32 v105, v105
	v_rcp_f32_e32 v108, v98
	v_exp_f32_e32 v90, v90
	v_mul_f32_e32 v91, 0xbfb8aa3b, v91
	s_or_b32 s72, s70, 3
	v_exp_f32_e32 v91, v91
	s_ashr_i32 s73, s72, 31
	s_lshl_b64 s[72:73], s[72:73], 13
	v_cvt_pk_bf16_f32 v98, v102, v103
	v_cvt_pk_bf16_f32 v99, v104, v105
	v_cvt_pk_bf16_f32 v100, v106, v101
	v_cvt_pk_bf16_f32 v101, v107, v108
	v_lshl_add_u64 v[102:103], v[126:127], 0, s[72:73]
	v_add_f32_e32 v90, 1.0, v90
	global_store_dwordx4 v[102:103], v[98:101], off nt
	v_mul_f32_e32 v94, 0xbfb8aa3b, v94
	v_mul_f32_e32 v95, 0xbfb8aa3b, v95
	v_rcp_f32_e32 v98, v90
	v_add_f32_e32 v90, 1.0, v91
	v_mul_f32_e32 v91, 0xbfb8aa3b, v92
	v_mul_f32_e32 v96, 0xbfb8aa3b, v96
	v_mul_f32_e32 v97, 0xbfb8aa3b, v97
	v_exp_f32_e32 v91, v91
	v_mul_f32_e32 v92, 0xbfb8aa3b, v93
	v_exp_f32_e32 v94, v94
	v_exp_f32_e32 v95, v95
	v_exp_f32_e32 v96, v96
	v_exp_f32_e32 v97, v97
	v_exp_f32_e32 v92, v92
	v_rcp_f32_e32 v93, v90
	v_add_f32_e32 v90, 1.0, v91
	v_add_f32_e32 v94, 1.0, v94
	v_add_f32_e32 v95, 1.0, v95
	v_add_f32_e32 v96, 1.0, v96
	v_add_f32_e32 v97, 1.0, v97
	v_rcp_f32_e32 v99, v90
	v_add_f32_e32 v90, 1.0, v92
	v_mul_f32_e32 v82, 0xbfb8aa3b, v82
	v_rcp_f32_e32 v94, v94
	v_rcp_f32_e32 v95, v95
	v_rcp_f32_e32 v96, v96
	v_rcp_f32_e32 v97, v97
	v_rcp_f32_e32 v100, v90
	v_exp_f32_e32 v82, v82
	v_mul_f32_e32 v83, 0xbfb8aa3b, v83
	s_or_b32 s72, s70, 4
	v_exp_f32_e32 v83, v83
	s_ashr_i32 s73, s72, 31
	s_lshl_b64 s[72:73], s[72:73], 13
	v_cvt_pk_bf16_f32 v90, v94, v95
	v_cvt_pk_bf16_f32 v91, v96, v97
	v_cvt_pk_bf16_f32 v92, v98, v93
	v_cvt_pk_bf16_f32 v93, v99, v100
	v_lshl_add_u64 v[94:95], v[126:127], 0, s[72:73]
	v_add_f32_e32 v82, 1.0, v82
	global_store_dwordx4 v[94:95], v[90:93], off nt
	v_mul_f32_e32 v86, 0xbfb8aa3b, v86
	v_mul_f32_e32 v87, 0xbfb8aa3b, v87
	v_rcp_f32_e32 v90, v82
	v_add_f32_e32 v82, 1.0, v83
	v_mul_f32_e32 v83, 0xbfb8aa3b, v84
	v_mul_f32_e32 v88, 0xbfb8aa3b, v88
	v_mul_f32_e32 v89, 0xbfb8aa3b, v89
	v_exp_f32_e32 v83, v83
	v_mul_f32_e32 v84, 0xbfb8aa3b, v85
	v_exp_f32_e32 v86, v86
	v_exp_f32_e32 v87, v87
	v_exp_f32_e32 v88, v88
	v_exp_f32_e32 v89, v89
	v_exp_f32_e32 v84, v84
	v_rcp_f32_e32 v85, v82
	v_add_f32_e32 v82, 1.0, v83
	v_add_f32_e32 v86, 1.0, v86
	v_add_f32_e32 v87, 1.0, v87
	v_add_f32_e32 v88, 1.0, v88
	v_add_f32_e32 v89, 1.0, v89
	v_rcp_f32_e32 v91, v82
	v_add_f32_e32 v82, 1.0, v84
	v_mul_f32_e32 v74, 0xbfb8aa3b, v74
	v_rcp_f32_e32 v86, v86
	v_rcp_f32_e32 v87, v87
	v_rcp_f32_e32 v88, v88
	v_rcp_f32_e32 v89, v89
	v_rcp_f32_e32 v92, v82
	v_exp_f32_e32 v74, v74
	v_mul_f32_e32 v75, 0xbfb8aa3b, v75
	s_or_b32 s72, s70, 5
	v_exp_f32_e32 v75, v75
	s_ashr_i32 s73, s72, 31
	s_lshl_b64 s[72:73], s[72:73], 13
	v_cvt_pk_bf16_f32 v82, v86, v87
	v_cvt_pk_bf16_f32 v83, v88, v89
	v_cvt_pk_bf16_f32 v84, v90, v85
	v_cvt_pk_bf16_f32 v85, v91, v92
	v_lshl_add_u64 v[86:87], v[126:127], 0, s[72:73]
	v_add_f32_e32 v74, 1.0, v74
	global_store_dwordx4 v[86:87], v[82:85], off nt
	v_mul_f32_e32 v78, 0xbfb8aa3b, v78
	v_mul_f32_e32 v79, 0xbfb8aa3b, v79
	v_rcp_f32_e32 v82, v74
	v_add_f32_e32 v74, 1.0, v75
	v_mul_f32_e32 v75, 0xbfb8aa3b, v76
	v_mul_f32_e32 v80, 0xbfb8aa3b, v80
	v_mul_f32_e32 v81, 0xbfb8aa3b, v81
	v_exp_f32_e32 v75, v75
	v_mul_f32_e32 v76, 0xbfb8aa3b, v77
	v_exp_f32_e32 v78, v78
	v_exp_f32_e32 v79, v79
	v_exp_f32_e32 v80, v80
	v_exp_f32_e32 v81, v81
	v_exp_f32_e32 v76, v76
	v_rcp_f32_e32 v77, v74
	v_add_f32_e32 v74, 1.0, v75
	v_add_f32_e32 v78, 1.0, v78
	v_add_f32_e32 v79, 1.0, v79
	v_add_f32_e32 v80, 1.0, v80
	v_add_f32_e32 v81, 1.0, v81
	v_rcp_f32_e32 v83, v74
	v_add_f32_e32 v74, 1.0, v76
	v_mul_f32_e32 v66, 0xbfb8aa3b, v66
	v_rcp_f32_e32 v78, v78
	v_rcp_f32_e32 v79, v79
	v_rcp_f32_e32 v80, v80
	v_rcp_f32_e32 v81, v81
	v_rcp_f32_e32 v84, v74
	v_exp_f32_e32 v66, v66
	v_mul_f32_e32 v67, 0xbfb8aa3b, v67
	s_or_b32 s72, s70, 6
	v_exp_f32_e32 v67, v67
	s_ashr_i32 s73, s72, 31
	s_lshl_b64 s[72:73], s[72:73], 13
	v_cvt_pk_bf16_f32 v74, v78, v79
	v_cvt_pk_bf16_f32 v75, v80, v81
	v_cvt_pk_bf16_f32 v76, v82, v77
	v_cvt_pk_bf16_f32 v77, v83, v84
	v_lshl_add_u64 v[78:79], v[126:127], 0, s[72:73]
	v_add_f32_e32 v66, 1.0, v66
	global_store_dwordx4 v[78:79], v[74:77], off nt
	v_mul_f32_e32 v70, 0xbfb8aa3b, v70
	v_mul_f32_e32 v71, 0xbfb8aa3b, v71
	v_rcp_f32_e32 v74, v66
	v_add_f32_e32 v66, 1.0, v67
	v_mul_f32_e32 v67, 0xbfb8aa3b, v68
	v_mul_f32_e32 v72, 0xbfb8aa3b, v72
	v_mul_f32_e32 v73, 0xbfb8aa3b, v73
	v_exp_f32_e32 v67, v67
	v_mul_f32_e32 v68, 0xbfb8aa3b, v69
	v_exp_f32_e32 v70, v70
	v_exp_f32_e32 v71, v71
	v_exp_f32_e32 v72, v72
	v_exp_f32_e32 v73, v73
	v_exp_f32_e32 v68, v68
	v_rcp_f32_e32 v69, v66
	v_add_f32_e32 v66, 1.0, v67
	v_add_f32_e32 v70, 1.0, v70
	v_add_f32_e32 v71, 1.0, v71
	v_add_f32_e32 v72, 1.0, v72
	v_add_f32_e32 v73, 1.0, v73
	v_rcp_f32_e32 v75, v66
	v_add_f32_e32 v66, 1.0, v68
	v_mul_f32_e32 v58, 0xbfb8aa3b, v58
	v_rcp_f32_e32 v70, v70
	v_rcp_f32_e32 v71, v71
	v_rcp_f32_e32 v72, v72
	v_rcp_f32_e32 v73, v73
	v_rcp_f32_e32 v76, v66
	v_exp_f32_e32 v58, v58
	v_mul_f32_e32 v59, 0xbfb8aa3b, v59
	s_or_b32 s72, s70, 7
	v_exp_f32_e32 v59, v59
	s_ashr_i32 s73, s72, 31
	s_lshl_b64 s[72:73], s[72:73], 13
	v_cvt_pk_bf16_f32 v66, v70, v71
	v_cvt_pk_bf16_f32 v67, v72, v73
	v_cvt_pk_bf16_f32 v68, v74, v69
	v_cvt_pk_bf16_f32 v69, v75, v76
	v_lshl_add_u64 v[70:71], v[126:127], 0, s[72:73]
	v_add_f32_e32 v58, 1.0, v58
	global_store_dwordx4 v[70:71], v[66:69], off nt
	v_mul_f32_e32 v62, 0xbfb8aa3b, v62
	v_mul_f32_e32 v63, 0xbfb8aa3b, v63
	v_rcp_f32_e32 v66, v58
	v_add_f32_e32 v58, 1.0, v59
	v_mul_f32_e32 v59, 0xbfb8aa3b, v60
	v_mul_f32_e32 v64, 0xbfb8aa3b, v64
	v_mul_f32_e32 v65, 0xbfb8aa3b, v65
	v_exp_f32_e32 v59, v59
	v_mul_f32_e32 v60, 0xbfb8aa3b, v61
	v_exp_f32_e32 v62, v62
	v_exp_f32_e32 v63, v63
	v_exp_f32_e32 v64, v64
	v_exp_f32_e32 v65, v65
	v_exp_f32_e32 v60, v60
	v_rcp_f32_e32 v61, v58
	v_add_f32_e32 v58, 1.0, v59
	v_add_f32_e32 v62, 1.0, v62
	v_add_f32_e32 v63, 1.0, v63
	v_add_f32_e32 v64, 1.0, v64
	v_add_f32_e32 v65, 1.0, v65
	v_rcp_f32_e32 v67, v58
	v_add_f32_e32 v58, 1.0, v60
	v_mul_f32_e32 v50, 0xbfb8aa3b, v50
	v_rcp_f32_e32 v62, v62
	v_rcp_f32_e32 v63, v63
	v_rcp_f32_e32 v64, v64
	v_rcp_f32_e32 v65, v65
	v_rcp_f32_e32 v68, v58
	v_exp_f32_e32 v50, v50
	v_mul_f32_e32 v51, 0xbfb8aa3b, v51
	s_or_b32 s72, s70, 8
	v_exp_f32_e32 v51, v51
	s_ashr_i32 s73, s72, 31
	s_lshl_b64 s[72:73], s[72:73], 13
	v_cvt_pk_bf16_f32 v58, v62, v63
	v_cvt_pk_bf16_f32 v59, v64, v65
	v_cvt_pk_bf16_f32 v60, v66, v61
	v_cvt_pk_bf16_f32 v61, v67, v68
	v_lshl_add_u64 v[62:63], v[126:127], 0, s[72:73]
	v_add_f32_e32 v50, 1.0, v50
	global_store_dwordx4 v[62:63], v[58:61], off nt
	v_mul_f32_e32 v54, 0xbfb8aa3b, v54
	v_mul_f32_e32 v55, 0xbfb8aa3b, v55
	v_rcp_f32_e32 v58, v50
	v_add_f32_e32 v50, 1.0, v51
	v_mul_f32_e32 v51, 0xbfb8aa3b, v52
	v_mul_f32_e32 v56, 0xbfb8aa3b, v56
	v_mul_f32_e32 v57, 0xbfb8aa3b, v57
	v_exp_f32_e32 v51, v51
	v_mul_f32_e32 v52, 0xbfb8aa3b, v53
	v_exp_f32_e32 v54, v54
	v_exp_f32_e32 v55, v55
	v_exp_f32_e32 v56, v56
	v_exp_f32_e32 v57, v57
	v_exp_f32_e32 v52, v52
	v_rcp_f32_e32 v53, v50
	v_add_f32_e32 v50, 1.0, v51
	v_add_f32_e32 v54, 1.0, v54
	v_add_f32_e32 v55, 1.0, v55
	v_add_f32_e32 v56, 1.0, v56
	v_add_f32_e32 v57, 1.0, v57
	v_rcp_f32_e32 v59, v50
	v_add_f32_e32 v50, 1.0, v52
	v_mul_f32_e32 v42, 0xbfb8aa3b, v42
	v_rcp_f32_e32 v54, v54
	v_rcp_f32_e32 v55, v55
	v_rcp_f32_e32 v56, v56
	v_rcp_f32_e32 v57, v57
	v_rcp_f32_e32 v60, v50
	v_exp_f32_e32 v42, v42
	v_mul_f32_e32 v43, 0xbfb8aa3b, v43
	s_or_b32 s72, s70, 9
	v_exp_f32_e32 v43, v43
	s_ashr_i32 s73, s72, 31
	s_lshl_b64 s[72:73], s[72:73], 13
	v_cvt_pk_bf16_f32 v50, v54, v55
	v_cvt_pk_bf16_f32 v51, v56, v57
	v_cvt_pk_bf16_f32 v52, v58, v53
	v_cvt_pk_bf16_f32 v53, v59, v60
	v_lshl_add_u64 v[54:55], v[126:127], 0, s[72:73]
	v_add_f32_e32 v42, 1.0, v42
	global_store_dwordx4 v[54:55], v[50:53], off nt
	v_mul_f32_e32 v46, 0xbfb8aa3b, v46
	v_mul_f32_e32 v47, 0xbfb8aa3b, v47
	v_rcp_f32_e32 v50, v42
	v_add_f32_e32 v42, 1.0, v43
	v_mul_f32_e32 v43, 0xbfb8aa3b, v44
	v_mul_f32_e32 v48, 0xbfb8aa3b, v48
	v_mul_f32_e32 v49, 0xbfb8aa3b, v49
	v_exp_f32_e32 v43, v43
	v_mul_f32_e32 v44, 0xbfb8aa3b, v45
	v_exp_f32_e32 v46, v46
	v_exp_f32_e32 v47, v47
	v_exp_f32_e32 v48, v48
	v_exp_f32_e32 v49, v49
	v_exp_f32_e32 v44, v44
	v_rcp_f32_e32 v45, v42
	v_add_f32_e32 v42, 1.0, v43
	v_add_f32_e32 v46, 1.0, v46
	v_add_f32_e32 v47, 1.0, v47
	v_add_f32_e32 v48, 1.0, v48
	v_add_f32_e32 v49, 1.0, v49
	v_rcp_f32_e32 v51, v42
	v_add_f32_e32 v42, 1.0, v44
	v_mul_f32_e32 v34, 0xbfb8aa3b, v34
	v_rcp_f32_e32 v46, v46
	v_rcp_f32_e32 v47, v47
	v_rcp_f32_e32 v48, v48
	v_rcp_f32_e32 v49, v49
	v_rcp_f32_e32 v52, v42
	v_exp_f32_e32 v34, v34
	v_mul_f32_e32 v35, 0xbfb8aa3b, v35
	s_or_b32 s72, s70, 10
	v_exp_f32_e32 v35, v35
	s_ashr_i32 s73, s72, 31
	s_lshl_b64 s[72:73], s[72:73], 13
	v_cvt_pk_bf16_f32 v42, v46, v47
	v_cvt_pk_bf16_f32 v43, v48, v49
	v_cvt_pk_bf16_f32 v44, v50, v45
	v_cvt_pk_bf16_f32 v45, v51, v52
	v_lshl_add_u64 v[46:47], v[126:127], 0, s[72:73]
	v_add_f32_e32 v34, 1.0, v34
	global_store_dwordx4 v[46:47], v[42:45], off nt
	v_mul_f32_e32 v38, 0xbfb8aa3b, v38
	v_mul_f32_e32 v39, 0xbfb8aa3b, v39
	v_rcp_f32_e32 v42, v34
	v_add_f32_e32 v34, 1.0, v35
	v_mul_f32_e32 v35, 0xbfb8aa3b, v36
	v_mul_f32_e32 v40, 0xbfb8aa3b, v40
	v_mul_f32_e32 v41, 0xbfb8aa3b, v41
	v_exp_f32_e32 v35, v35
	v_mul_f32_e32 v36, 0xbfb8aa3b, v37
	v_exp_f32_e32 v38, v38
	v_exp_f32_e32 v39, v39
	v_exp_f32_e32 v40, v40
	v_exp_f32_e32 v41, v41
	v_exp_f32_e32 v36, v36
	v_rcp_f32_e32 v37, v34
	v_add_f32_e32 v34, 1.0, v35
	v_add_f32_e32 v38, 1.0, v38
	v_add_f32_e32 v39, 1.0, v39
	v_add_f32_e32 v40, 1.0, v40
	v_add_f32_e32 v41, 1.0, v41
	v_rcp_f32_e32 v43, v34
	v_add_f32_e32 v34, 1.0, v36
	v_mul_f32_e32 v26, 0xbfb8aa3b, v26
	v_rcp_f32_e32 v38, v38
	v_rcp_f32_e32 v39, v39
	v_rcp_f32_e32 v40, v40
	v_rcp_f32_e32 v41, v41
	v_rcp_f32_e32 v44, v34
	v_exp_f32_e32 v26, v26
	v_mul_f32_e32 v27, 0xbfb8aa3b, v27
	s_or_b32 s72, s70, 11
	v_exp_f32_e32 v27, v27
	s_ashr_i32 s73, s72, 31
	s_lshl_b64 s[72:73], s[72:73], 13
	v_cvt_pk_bf16_f32 v34, v38, v39
	v_cvt_pk_bf16_f32 v35, v40, v41
	v_cvt_pk_bf16_f32 v36, v42, v37
	v_cvt_pk_bf16_f32 v37, v43, v44
	v_lshl_add_u64 v[38:39], v[126:127], 0, s[72:73]
	v_add_f32_e32 v26, 1.0, v26
	global_store_dwordx4 v[38:39], v[34:37], off nt
	v_mul_f32_e32 v30, 0xbfb8aa3b, v30
	v_mul_f32_e32 v31, 0xbfb8aa3b, v31
	v_rcp_f32_e32 v34, v26
	v_add_f32_e32 v26, 1.0, v27
	v_mul_f32_e32 v27, 0xbfb8aa3b, v28
	v_mul_f32_e32 v32, 0xbfb8aa3b, v32
	v_mul_f32_e32 v33, 0xbfb8aa3b, v33
	v_exp_f32_e32 v27, v27
	v_mul_f32_e32 v28, 0xbfb8aa3b, v29
	v_exp_f32_e32 v30, v30
	v_exp_f32_e32 v31, v31
	v_exp_f32_e32 v32, v32
	v_exp_f32_e32 v33, v33
	v_exp_f32_e32 v28, v28
	v_rcp_f32_e32 v29, v26
	v_add_f32_e32 v26, 1.0, v27
	v_add_f32_e32 v30, 1.0, v30
	v_add_f32_e32 v31, 1.0, v31
	v_add_f32_e32 v32, 1.0, v32
	v_add_f32_e32 v33, 1.0, v33
	v_rcp_f32_e32 v35, v26
	v_add_f32_e32 v26, 1.0, v28
	v_mul_f32_e32 v18, 0xbfb8aa3b, v18
	v_rcp_f32_e32 v30, v30
	v_rcp_f32_e32 v31, v31
	v_rcp_f32_e32 v32, v32
	v_rcp_f32_e32 v33, v33
	v_rcp_f32_e32 v36, v26
	v_exp_f32_e32 v18, v18
	v_mul_f32_e32 v19, 0xbfb8aa3b, v19
	s_or_b32 s72, s70, 12
	v_exp_f32_e32 v19, v19
	s_ashr_i32 s73, s72, 31
	s_lshl_b64 s[72:73], s[72:73], 13
	v_cvt_pk_bf16_f32 v26, v30, v31
	v_cvt_pk_bf16_f32 v27, v32, v33
	v_cvt_pk_bf16_f32 v28, v34, v29
	v_cvt_pk_bf16_f32 v29, v35, v36
	v_lshl_add_u64 v[30:31], v[126:127], 0, s[72:73]
	v_add_f32_e32 v18, 1.0, v18
	global_store_dwordx4 v[30:31], v[26:29], off nt
	v_mul_f32_e32 v22, 0xbfb8aa3b, v22
	v_mul_f32_e32 v23, 0xbfb8aa3b, v23
	v_rcp_f32_e32 v26, v18
	v_add_f32_e32 v18, 1.0, v19
	v_mul_f32_e32 v19, 0xbfb8aa3b, v20
	v_mul_f32_e32 v24, 0xbfb8aa3b, v24
	v_mul_f32_e32 v25, 0xbfb8aa3b, v25
	v_exp_f32_e32 v19, v19
	v_mul_f32_e32 v20, 0xbfb8aa3b, v21
	v_exp_f32_e32 v22, v22
	v_exp_f32_e32 v23, v23
	v_exp_f32_e32 v24, v24
	v_exp_f32_e32 v25, v25
	v_exp_f32_e32 v20, v20
	v_rcp_f32_e32 v21, v18
	v_add_f32_e32 v18, 1.0, v19
	v_add_f32_e32 v22, 1.0, v22
	v_add_f32_e32 v23, 1.0, v23
	v_add_f32_e32 v24, 1.0, v24
	v_add_f32_e32 v25, 1.0, v25
	v_rcp_f32_e32 v27, v18
	v_add_f32_e32 v18, 1.0, v20
	v_mul_f32_e32 v10, 0xbfb8aa3b, v10
	v_rcp_f32_e32 v22, v22
	v_rcp_f32_e32 v23, v23
	v_rcp_f32_e32 v24, v24
	v_rcp_f32_e32 v25, v25
	v_rcp_f32_e32 v28, v18
	v_exp_f32_e32 v10, v10
	v_mul_f32_e32 v11, 0xbfb8aa3b, v11
	s_or_b32 s72, s70, 13
	v_exp_f32_e32 v11, v11
	s_ashr_i32 s73, s72, 31
	s_lshl_b64 s[72:73], s[72:73], 13
	v_cvt_pk_bf16_f32 v18, v22, v23
	v_cvt_pk_bf16_f32 v19, v24, v25
	v_cvt_pk_bf16_f32 v20, v26, v21
	v_cvt_pk_bf16_f32 v21, v27, v28
	v_lshl_add_u64 v[22:23], v[126:127], 0, s[72:73]
	v_add_f32_e32 v10, 1.0, v10
	global_store_dwordx4 v[22:23], v[18:21], off nt
	v_mul_f32_e32 v14, 0xbfb8aa3b, v14
	v_mul_f32_e32 v15, 0xbfb8aa3b, v15
	v_rcp_f32_e32 v18, v10
	v_add_f32_e32 v10, 1.0, v11
	v_mul_f32_e32 v11, 0xbfb8aa3b, v12
	v_mul_f32_e32 v16, 0xbfb8aa3b, v16
	v_mul_f32_e32 v17, 0xbfb8aa3b, v17
	v_exp_f32_e32 v11, v11
	v_mul_f32_e32 v12, 0xbfb8aa3b, v13
	v_exp_f32_e32 v14, v14
	v_exp_f32_e32 v15, v15
	v_exp_f32_e32 v16, v16
	v_exp_f32_e32 v17, v17
	v_exp_f32_e32 v12, v12
	v_rcp_f32_e32 v13, v10
	v_add_f32_e32 v10, 1.0, v11
	v_add_f32_e32 v14, 1.0, v14
	v_add_f32_e32 v15, 1.0, v15
	v_add_f32_e32 v16, 1.0, v16
	v_add_f32_e32 v17, 1.0, v17
	v_rcp_f32_e32 v19, v10
	v_add_f32_e32 v10, 1.0, v12
	v_mul_f32_e32 v0, 0xbfb8aa3b, v0
	v_rcp_f32_e32 v14, v14
	v_rcp_f32_e32 v15, v15
	v_rcp_f32_e32 v16, v16
	v_rcp_f32_e32 v17, v17
	v_rcp_f32_e32 v20, v10
	v_exp_f32_e32 v0, v0
	v_mul_f32_e32 v1, 0xbfb8aa3b, v1
	s_or_b32 s72, s70, 14
	v_exp_f32_e32 v1, v1
	s_ashr_i32 s73, s72, 31
	s_lshl_b64 s[72:73], s[72:73], 13
	v_cvt_pk_bf16_f32 v10, v14, v15
	v_cvt_pk_bf16_f32 v11, v16, v17
	v_cvt_pk_bf16_f32 v12, v18, v13
	v_cvt_pk_bf16_f32 v13, v19, v20
	v_lshl_add_u64 v[14:15], v[126:127], 0, s[72:73]
	v_add_f32_e32 v0, 1.0, v0
	global_store_dwordx4 v[14:15], v[10:13], off nt
	v_mul_f32_e32 v6, 0xbfb8aa3b, v6
	v_mul_f32_e32 v7, 0xbfb8aa3b, v7
	v_rcp_f32_e32 v10, v0
	v_add_f32_e32 v0, 1.0, v1
	v_mul_f32_e32 v1, 0xbfb8aa3b, v2
	v_mul_f32_e32 v8, 0xbfb8aa3b, v8
	v_mul_f32_e32 v9, 0xbfb8aa3b, v9
	v_exp_f32_e32 v1, v1
	v_mul_f32_e32 v2, 0xbfb8aa3b, v3
	v_exp_f32_e32 v6, v6
	v_exp_f32_e32 v7, v7
	v_exp_f32_e32 v8, v8
	v_exp_f32_e32 v9, v9
	v_exp_f32_e32 v2, v2
	v_rcp_f32_e32 v3, v0
	v_add_f32_e32 v0, 1.0, v1
	v_add_f32_e32 v6, 1.0, v6
	v_add_f32_e32 v7, 1.0, v7
	v_add_f32_e32 v8, 1.0, v8
	v_add_f32_e32 v9, 1.0, v9
	v_rcp_f32_e32 v11, v0
	v_add_f32_e32 v0, 1.0, v2
	v_rcp_f32_e32 v6, v6
	v_rcp_f32_e32 v7, v7
	v_rcp_f32_e32 v8, v8
	v_rcp_f32_e32 v9, v9
	v_rcp_f32_e32 v12, v0
	s_or_b32 s70, s70, 15
	s_ashr_i32 s71, s70, 31
	s_lshl_b64 s[70:71], s[70:71], 13
	v_cvt_pk_bf16_f32 v0, v6, v7
	v_cvt_pk_bf16_f32 v1, v8, v9
	v_cvt_pk_bf16_f32 v2, v10, v3
	v_cvt_pk_bf16_f32 v3, v11, v12
	v_lshl_add_u64 v[6:7], v[126:127], 0, s[70:71]
	s_cmp_eq_u32 s61, 2
	s_mov_b64 s[70:71], -1
	global_store_dwordx4 v[6:7], v[0:3], off nt
	s_cbranch_scc1 .LBB0_1255
	s_andn2_b64 vcc, exec, s[4:5]
	s_cbranch_vccnz .LBB0_1254
	s_barrier
	s_branch .LBB0_1254

.Lmrg_seg0:
	s_mov_b64 s[70:71], s[72:73]
	v_mov_b32_e32 v230, 0
	v_mov_b32_e32 v231, 0
	s_add_u32 s4, s70, 0x0
	s_addc_u32 s5, s71, 0
	global_load_dwordx4 v[130:133], v232, s[4:5] nt
	s_add_u32 s4, s70, 0x2000
	s_addc_u32 s5, s71, 0
	global_load_dwordx4 v[134:137], v232, s[4:5] nt
	s_add_u32 s4, s70, 0x4000
	s_addc_u32 s5, s71, 0
	global_load_dwordx4 v[156:159], v232, s[4:5] nt
	s_add_u32 s4, s70, 0x6000
	s_addc_u32 s5, s71, 0
	global_load_dwordx4 v[162:165], v232, s[4:5] nt
	s_add_u32 s4, s70, 0x8000
	s_addc_u32 s5, s71, 0
	global_load_dwordx4 v[166:169], v232, s[4:5] nt
	s_add_u32 s4, s70, 0xa000
	s_addc_u32 s5, s71, 0
	global_load_dwordx4 v[170:173], v232, s[4:5] nt
	s_add_u32 s4, s70, 0xc000
	s_addc_u32 s5, s71, 0
	global_load_dwordx4 v[174:177], v232, s[4:5] nt
	s_add_u32 s4, s70, 0xe000
	s_addc_u32 s5, s71, 0
	global_load_dwordx4 v[178:181], v232, s[4:5] nt
	s_waitcnt vmcnt(7)
	v_lshlrev_b32_e32 v224, 16, v130
	v_and_b32_e32 v225, 0xffff0000, v130
	v_pk_fma_f32 v[126:127], v[126:127], v[224:225], v[230:231]
	v_lshlrev_b32_e32 v226, 16, v131
	v_and_b32_e32 v227, 0xffff0000, v131
	v_pk_fma_f32 v[128:129], v[128:129], v[226:227], v[230:231]
	v_lshlrev_b32_e32 v224, 16, v132
	v_and_b32_e32 v225, 0xffff0000, v132
	v_pk_fma_f32 v[122:123], v[122:123], v[224:225], v[230:231]
	v_lshlrev_b32_e32 v226, 16, v133
	v_and_b32_e32 v227, 0xffff0000, v133
	v_pk_fma_f32 v[124:125], v[124:125], v[226:227], v[230:231]
	v_cvt_pk_bf16_f32 v126, v126, v127
	v_cvt_pk_bf16_f32 v127, v128, v129
	v_cvt_pk_bf16_f32 v128, v122, v123
	v_cvt_pk_bf16_f32 v129, v124, v125
	s_add_u32 s76, s72, 0x0
	s_addc_u32 s77, s73, 0
	global_store_dwordx4 v232, v[126:129], s[76:77] nt
	s_add_u32 s4, s70, 0x10000
	s_addc_u32 s5, s71, 0
	global_load_dwordx4 v[130:133], v232, s[4:5] nt
	s_waitcnt vmcnt(8)
	v_lshlrev_b32_e32 v224, 16, v134
	v_and_b32_e32 v225, 0xffff0000, v134
	v_pk_fma_f32 v[118:119], v[118:119], v[224:225], v[230:231]
	v_lshlrev_b32_e32 v226, 16, v135
	v_and_b32_e32 v227, 0xffff0000, v135
	v_pk_fma_f32 v[120:121], v[120:121], v[226:227], v[230:231]
	v_lshlrev_b32_e32 v224, 16, v136
	v_and_b32_e32 v225, 0xffff0000, v136
	v_pk_fma_f32 v[114:115], v[114:115], v[224:225], v[230:231]
	v_lshlrev_b32_e32 v226, 16, v137
	v_and_b32_e32 v227, 0xffff0000, v137
	v_pk_fma_f32 v[116:117], v[116:117], v[226:227], v[230:231]
	v_cvt_pk_bf16_f32 v118, v118, v119
	v_cvt_pk_bf16_f32 v119, v120, v121
	v_cvt_pk_bf16_f32 v120, v114, v115
	v_cvt_pk_bf16_f32 v121, v116, v117
	s_add_u32 s76, s72, 0x2000
	s_addc_u32 s77, s73, 0
	global_store_dwordx4 v232, v[118:121], s[76:77] nt
	s_add_u32 s4, s70, 0x12000
	s_addc_u32 s5, s71, 0
	global_load_dwordx4 v[134:137], v232, s[4:5] nt
	s_waitcnt vmcnt(9)
	v_lshlrev_b32_e32 v224, 16, v156
	v_and_b32_e32 v225, 0xffff0000, v156
	v_pk_fma_f32 v[110:111], v[110:111], v[224:225], v[230:231]
	v_lshlrev_b32_e32 v226, 16, v157
	v_and_b32_e32 v227, 0xffff0000, v157
	v_pk_fma_f32 v[112:113], v[112:113], v[226:227], v[230:231]
	v_lshlrev_b32_e32 v224, 16, v158
	v_and_b32_e32 v225, 0xffff0000, v158
	v_pk_fma_f32 v[106:107], v[106:107], v[224:225], v[230:231]
	v_lshlrev_b32_e32 v226, 16, v159
	v_and_b32_e32 v227, 0xffff0000, v159
	v_pk_fma_f32 v[108:109], v[108:109], v[226:227], v[230:231]
	v_cvt_pk_bf16_f32 v110, v110, v111
	v_cvt_pk_bf16_f32 v111, v112, v113
	v_cvt_pk_bf16_f32 v112, v106, v107
	v_cvt_pk_bf16_f32 v113, v108, v109
	s_add_u32 s76, s72, 0x4000
	s_addc_u32 s77, s73, 0
	global_store_dwordx4 v232, v[110:113], s[76:77] nt
	s_add_u32 s4, s70, 0x14000
	s_addc_u32 s5, s71, 0
	global_load_dwordx4 v[156:159], v232, s[4:5] nt
	s_waitcnt vmcnt(10)
	v_lshlrev_b32_e32 v224, 16, v162
	v_and_b32_e32 v225, 0xffff0000, v162
	v_pk_fma_f32 v[102:103], v[102:103], v[224:225], v[230:231]
	v_lshlrev_b32_e32 v226, 16, v163
	v_and_b32_e32 v227, 0xffff0000, v163
	v_pk_fma_f32 v[104:105], v[104:105], v[226:227], v[230:231]
	v_lshlrev_b32_e32 v224, 16, v164
	v_and_b32_e32 v225, 0xffff0000, v164
	v_pk_fma_f32 v[98:99], v[98:99], v[224:225], v[230:231]
	v_lshlrev_b32_e32 v226, 16, v165
	v_and_b32_e32 v227, 0xffff0000, v165
	v_pk_fma_f32 v[100:101], v[100:101], v[226:227], v[230:231]
	v_cvt_pk_bf16_f32 v102, v102, v103
	v_cvt_pk_bf16_f32 v103, v104, v105
	v_cvt_pk_bf16_f32 v104, v98, v99
	v_cvt_pk_bf16_f32 v105, v100, v101
	s_add_u32 s76, s72, 0x6000
	s_addc_u32 s77, s73, 0
	global_store_dwordx4 v232, v[102:105], s[76:77] nt
	s_add_u32 s4, s70, 0x16000
	s_addc_u32 s5, s71, 0
	global_load_dwordx4 v[162:165], v232, s[4:5] nt
	s_waitcnt vmcnt(11)
	v_lshlrev_b32_e32 v224, 16, v166
	v_and_b32_e32 v225, 0xffff0000, v166
	v_pk_fma_f32 v[94:95], v[94:95], v[224:225], v[230:231]
	v_lshlrev_b32_e32 v226, 16, v167
	v_and_b32_e32 v227, 0xffff0000, v167
	v_pk_fma_f32 v[96:97], v[96:97], v[226:227], v[230:231]
	v_lshlrev_b32_e32 v224, 16, v168
	v_and_b32_e32 v225, 0xffff0000, v168
	v_pk_fma_f32 v[90:91], v[90:91], v[224:225], v[230:231]
	v_lshlrev_b32_e32 v226, 16, v169
	v_and_b32_e32 v227, 0xffff0000, v169
	v_pk_fma_f32 v[92:93], v[92:93], v[226:227], v[230:231]
	v_cvt_pk_bf16_f32 v94, v94, v95
	v_cvt_pk_bf16_f32 v95, v96, v97
	v_cvt_pk_bf16_f32 v96, v90, v91
	v_cvt_pk_bf16_f32 v97, v92, v93
	s_add_u32 s76, s72, 0x8000
	s_addc_u32 s77, s73, 0
	global_store_dwordx4 v232, v[94:97], s[76:77] nt
	s_add_u32 s4, s70, 0x18000
	s_addc_u32 s5, s71, 0
	global_load_dwordx4 v[166:169], v232, s[4:5] nt
	s_waitcnt vmcnt(12)
	v_lshlrev_b32_e32 v224, 16, v170
	v_and_b32_e32 v225, 0xffff0000, v170
	v_pk_fma_f32 v[86:87], v[86:87], v[224:225], v[230:231]
	v_lshlrev_b32_e32 v226, 16, v171
	v_and_b32_e32 v227, 0xffff0000, v171
	v_pk_fma_f32 v[88:89], v[88:89], v[226:227], v[230:231]
	v_lshlrev_b32_e32 v224, 16, v172
	v_and_b32_e32 v225, 0xffff0000, v172
	v_pk_fma_f32 v[82:83], v[82:83], v[224:225], v[230:231]
	v_lshlrev_b32_e32 v226, 16, v173
	v_and_b32_e32 v227, 0xffff0000, v173
	v_pk_fma_f32 v[84:85], v[84:85], v[226:227], v[230:231]
	v_cvt_pk_bf16_f32 v86, v86, v87
	v_cvt_pk_bf16_f32 v87, v88, v89
	v_cvt_pk_bf16_f32 v88, v82, v83
	v_cvt_pk_bf16_f32 v89, v84, v85
	s_add_u32 s76, s72, 0xa000
	s_addc_u32 s77, s73, 0
	global_store_dwordx4 v232, v[86:89], s[76:77] nt
	s_add_u32 s4, s70, 0x1a000
	s_addc_u32 s5, s71, 0
	global_load_dwordx4 v[170:173], v232, s[4:5] nt
	s_waitcnt vmcnt(13)
	v_lshlrev_b32_e32 v224, 16, v174
	v_and_b32_e32 v225, 0xffff0000, v174
	v_pk_fma_f32 v[78:79], v[78:79], v[224:225], v[230:231]
	v_lshlrev_b32_e32 v226, 16, v175
	v_and_b32_e32 v227, 0xffff0000, v175
	v_pk_fma_f32 v[80:81], v[80:81], v[226:227], v[230:231]
	v_lshlrev_b32_e32 v224, 16, v176
	v_and_b32_e32 v225, 0xffff0000, v176
	v_pk_fma_f32 v[74:75], v[74:75], v[224:225], v[230:231]
	v_lshlrev_b32_e32 v226, 16, v177
	v_and_b32_e32 v227, 0xffff0000, v177
	v_pk_fma_f32 v[76:77], v[76:77], v[226:227], v[230:231]
	v_cvt_pk_bf16_f32 v78, v78, v79
	v_cvt_pk_bf16_f32 v79, v80, v81
	v_cvt_pk_bf16_f32 v80, v74, v75
	v_cvt_pk_bf16_f32 v81, v76, v77
	s_add_u32 s76, s72, 0xc000
	s_addc_u32 s77, s73, 0
	global_store_dwordx4 v232, v[78:81], s[76:77] nt
	s_add_u32 s4, s70, 0x1c000
	s_addc_u32 s5, s71, 0
	global_load_dwordx4 v[174:177], v232, s[4:5] nt
	s_waitcnt vmcnt(14)
	v_lshlrev_b32_e32 v224, 16, v178
	v_and_b32_e32 v225, 0xffff0000, v178
	v_pk_fma_f32 v[70:71], v[70:71], v[224:225], v[230:231]
	v_lshlrev_b32_e32 v226, 16, v179
	v_and_b32_e32 v227, 0xffff0000, v179
	v_pk_fma_f32 v[72:73], v[72:73], v[226:227], v[230:231]
	v_lshlrev_b32_e32 v224, 16, v180
	v_and_b32_e32 v225, 0xffff0000, v180
	v_pk_fma_f32 v[66:67], v[66:67], v[224:225], v[230:231]
	v_lshlrev_b32_e32 v226, 16, v181
	v_and_b32_e32 v227, 0xffff0000, v181
	v_pk_fma_f32 v[68:69], v[68:69], v[226:227], v[230:231]
	v_cvt_pk_bf16_f32 v70, v70, v71
	v_cvt_pk_bf16_f32 v71, v72, v73
	v_cvt_pk_bf16_f32 v72, v66, v67
	v_cvt_pk_bf16_f32 v73, v68, v69
	s_add_u32 s76, s72, 0xe000
	s_addc_u32 s77, s73, 0
	global_store_dwordx4 v232, v[70:73], s[76:77] nt
	s_add_u32 s4, s70, 0x1e000
	s_addc_u32 s5, s71, 0
	global_load_dwordx4 v[178:181], v232, s[4:5] nt
	s_waitcnt vmcnt(14)
	v_lshlrev_b32_e32 v224, 16, v130
	v_and_b32_e32 v225, 0xffff0000, v130
	v_pk_fma_f32 v[62:63], v[62:63], v[224:225], v[230:231]
	v_lshlrev_b32_e32 v226, 16, v131
	v_and_b32_e32 v227, 0xffff0000, v131
	v_pk_fma_f32 v[64:65], v[64:65], v[226:227], v[230:231]
	v_lshlrev_b32_e32 v224, 16, v132
	v_and_b32_e32 v225, 0xffff0000, v132
	v_pk_fma_f32 v[58:59], v[58:59], v[224:225], v[230:231]
	v_lshlrev_b32_e32 v226, 16, v133
	v_and_b32_e32 v227, 0xffff0000, v133
	v_pk_fma_f32 v[60:61], v[60:61], v[226:227], v[230:231]
	v_cvt_pk_bf16_f32 v62, v62, v63
	v_cvt_pk_bf16_f32 v63, v64, v65
	v_cvt_pk_bf16_f32 v64, v58, v59
	v_cvt_pk_bf16_f32 v65, v60, v61
	s_add_u32 s76, s72, 0x10000
	s_addc_u32 s77, s73, 0
	global_store_dwordx4 v232, v[62:65], s[76:77] nt
	s_waitcnt vmcnt(13)
	v_lshlrev_b32_e32 v224, 16, v134
	v_and_b32_e32 v225, 0xffff0000, v134
	v_pk_fma_f32 v[54:55], v[54:55], v[224:225], v[230:231]
	v_lshlrev_b32_e32 v226, 16, v135
	v_and_b32_e32 v227, 0xffff0000, v135
	v_pk_fma_f32 v[56:57], v[56:57], v[226:227], v[230:231]
	v_lshlrev_b32_e32 v224, 16, v136
	v_and_b32_e32 v225, 0xffff0000, v136
	v_pk_fma_f32 v[50:51], v[50:51], v[224:225], v[230:231]
	v_lshlrev_b32_e32 v226, 16, v137
	v_and_b32_e32 v227, 0xffff0000, v137
	v_pk_fma_f32 v[52:53], v[52:53], v[226:227], v[230:231]
	v_cvt_pk_bf16_f32 v54, v54, v55
	v_cvt_pk_bf16_f32 v55, v56, v57
	v_cvt_pk_bf16_f32 v56, v50, v51
	v_cvt_pk_bf16_f32 v57, v52, v53
	s_add_u32 s76, s72, 0x12000
	s_addc_u32 s77, s73, 0
	global_store_dwordx4 v232, v[54:57], s[76:77] nt
	s_waitcnt vmcnt(12)
	v_lshlrev_b32_e32 v224, 16, v156
	v_and_b32_e32 v225, 0xffff0000, v156
	v_pk_fma_f32 v[46:47], v[46:47], v[224:225], v[230:231]
	v_lshlrev_b32_e32 v226, 16, v157
	v_and_b32_e32 v227, 0xffff0000, v157
	v_pk_fma_f32 v[48:49], v[48:49], v[226:227], v[230:231]
	v_lshlrev_b32_e32 v224, 16, v158
	v_and_b32_e32 v225, 0xffff0000, v158
	v_pk_fma_f32 v[42:43], v[42:43], v[224:225], v[230:231]
	v_lshlrev_b32_e32 v226, 16, v159
	v_and_b32_e32 v227, 0xffff0000, v159
	v_pk_fma_f32 v[44:45], v[44:45], v[226:227], v[230:231]
	v_cvt_pk_bf16_f32 v46, v46, v47
	v_cvt_pk_bf16_f32 v47, v48, v49
	v_cvt_pk_bf16_f32 v48, v42, v43
	v_cvt_pk_bf16_f32 v49, v44, v45
	s_add_u32 s76, s72, 0x14000
	s_addc_u32 s77, s73, 0
	global_store_dwordx4 v232, v[46:49], s[76:77] nt
	s_waitcnt vmcnt(11)
	v_lshlrev_b32_e32 v224, 16, v162
	v_and_b32_e32 v225, 0xffff0000, v162
	v_pk_fma_f32 v[38:39], v[38:39], v[224:225], v[230:231]
	v_lshlrev_b32_e32 v226, 16, v163
	v_and_b32_e32 v227, 0xffff0000, v163
	v_pk_fma_f32 v[40:41], v[40:41], v[226:227], v[230:231]
	v_lshlrev_b32_e32 v224, 16, v164
	v_and_b32_e32 v225, 0xffff0000, v164
	v_pk_fma_f32 v[34:35], v[34:35], v[224:225], v[230:231]
	v_lshlrev_b32_e32 v226, 16, v165
	v_and_b32_e32 v227, 0xffff0000, v165
	v_pk_fma_f32 v[36:37], v[36:37], v[226:227], v[230:231]
	v_cvt_pk_bf16_f32 v38, v38, v39
	v_cvt_pk_bf16_f32 v39, v40, v41
	v_cvt_pk_bf16_f32 v40, v34, v35
	v_cvt_pk_bf16_f32 v41, v36, v37
	s_add_u32 s76, s72, 0x16000
	s_addc_u32 s77, s73, 0
	global_store_dwordx4 v232, v[38:41], s[76:77] nt
	s_waitcnt vmcnt(10)
	v_lshlrev_b32_e32 v224, 16, v166
	v_and_b32_e32 v225, 0xffff0000, v166
	v_pk_fma_f32 v[30:31], v[30:31], v[224:225], v[230:231]
	v_lshlrev_b32_e32 v226, 16, v167
	v_and_b32_e32 v227, 0xffff0000, v167
	v_pk_fma_f32 v[32:33], v[32:33], v[226:227], v[230:231]
	v_lshlrev_b32_e32 v224, 16, v168
	v_and_b32_e32 v225, 0xffff0000, v168
	v_pk_fma_f32 v[26:27], v[26:27], v[224:225], v[230:231]
	v_lshlrev_b32_e32 v226, 16, v169
	v_and_b32_e32 v227, 0xffff0000, v169
	v_pk_fma_f32 v[28:29], v[28:29], v[226:227], v[230:231]
	v_cvt_pk_bf16_f32 v30, v30, v31
	v_cvt_pk_bf16_f32 v31, v32, v33
	v_cvt_pk_bf16_f32 v32, v26, v27
	v_cvt_pk_bf16_f32 v33, v28, v29
	s_add_u32 s76, s72, 0x18000
	s_addc_u32 s77, s73, 0
	global_store_dwordx4 v232, v[30:33], s[76:77] nt
	s_waitcnt vmcnt(9)
	v_lshlrev_b32_e32 v224, 16, v170
	v_and_b32_e32 v225, 0xffff0000, v170
	v_pk_fma_f32 v[22:23], v[22:23], v[224:225], v[230:231]
	v_lshlrev_b32_e32 v226, 16, v171
	v_and_b32_e32 v227, 0xffff0000, v171
	v_pk_fma_f32 v[24:25], v[24:25], v[226:227], v[230:231]
	v_lshlrev_b32_e32 v224, 16, v172
	v_and_b32_e32 v225, 0xffff0000, v172
	v_pk_fma_f32 v[18:19], v[18:19], v[224:225], v[230:231]
	v_lshlrev_b32_e32 v226, 16, v173
	v_and_b32_e32 v227, 0xffff0000, v173
	v_pk_fma_f32 v[20:21], v[20:21], v[226:227], v[230:231]
	v_cvt_pk_bf16_f32 v22, v22, v23
	v_cvt_pk_bf16_f32 v23, v24, v25
	v_cvt_pk_bf16_f32 v24, v18, v19
	v_cvt_pk_bf16_f32 v25, v20, v21
	s_add_u32 s76, s72, 0x1a000
	s_addc_u32 s77, s73, 0
	global_store_dwordx4 v232, v[22:25], s[76:77] nt
	s_waitcnt vmcnt(8)
	v_lshlrev_b32_e32 v224, 16, v174
	v_and_b32_e32 v225, 0xffff0000, v174
	v_pk_fma_f32 v[14:15], v[14:15], v[224:225], v[230:231]
	v_lshlrev_b32_e32 v226, 16, v175
	v_and_b32_e32 v227, 0xffff0000, v175
	v_pk_fma_f32 v[16:17], v[16:17], v[226:227], v[230:231]
	v_lshlrev_b32_e32 v224, 16, v176
	v_and_b32_e32 v225, 0xffff0000, v176
	v_pk_fma_f32 v[10:11], v[10:11], v[224:225], v[230:231]
	v_lshlrev_b32_e32 v226, 16, v177
	v_and_b32_e32 v227, 0xffff0000, v177
	v_pk_fma_f32 v[12:13], v[12:13], v[226:227], v[230:231]
	v_cvt_pk_bf16_f32 v14, v14, v15
	v_cvt_pk_bf16_f32 v15, v16, v17
	v_cvt_pk_bf16_f32 v16, v10, v11
	v_cvt_pk_bf16_f32 v17, v12, v13
	s_add_u32 s76, s72, 0x1c000
	s_addc_u32 s77, s73, 0
	global_store_dwordx4 v232, v[14:17], s[76:77] nt
	s_waitcnt vmcnt(7)
	v_lshlrev_b32_e32 v224, 16, v178
	v_and_b32_e32 v225, 0xffff0000, v178
	v_pk_fma_f32 v[6:7], v[6:7], v[224:225], v[230:231]
	v_lshlrev_b32_e32 v226, 16, v179
	v_and_b32_e32 v227, 0xffff0000, v179
	v_pk_fma_f32 v[8:9], v[8:9], v[226:227], v[230:231]
	v_lshlrev_b32_e32 v224, 16, v180
	v_and_b32_e32 v225, 0xffff0000, v180
	v_pk_fma_f32 v[0:1], v[0:1], v[224:225], v[230:231]
	v_lshlrev_b32_e32 v226, 16, v181
	v_and_b32_e32 v227, 0xffff0000, v181
	v_pk_fma_f32 v[2:3], v[2:3], v[226:227], v[230:231]
	v_cvt_pk_bf16_f32 v6, v6, v7
	v_cvt_pk_bf16_f32 v7, v8, v9
	v_cvt_pk_bf16_f32 v8, v0, v1
	v_cvt_pk_bf16_f32 v9, v2, v3
	s_add_u32 s76, s72, 0x1e000
	s_addc_u32 s77, s73, 0
	global_store_dwordx4 v232, v[6:9], s[76:77] nt
	s_branch .Lmrg_done
.Lmrg_seg1:
	s_add_u32 s70, s26, 0x4512000
	s_addc_u32 s71, s27, 0
	s_add_u32 s70, s70, s4
	s_addc_u32 s71, s71, 0
	s_add_u32 s4, s70, 0x0
	s_addc_u32 s5, s71, 0
	global_load_dwordx4 v[130:133], v232, s[4:5] nt
	s_add_u32 s4, s72, 0x0
	s_addc_u32 s5, s73, 0
	global_load_dwordx4 v[182:185], v232, s[4:5] nt
	s_add_u32 s4, s70, 0x2000
	s_addc_u32 s5, s71, 0
	global_load_dwordx4 v[134:137], v232, s[4:5] nt
	s_add_u32 s4, s72, 0x2000
	s_addc_u32 s5, s73, 0
	global_load_dwordx4 v[186:189], v232, s[4:5] nt
	s_add_u32 s4, s70, 0x4000
	s_addc_u32 s5, s71, 0
	global_load_dwordx4 v[156:159], v232, s[4:5] nt
	s_add_u32 s4, s72, 0x4000
	s_addc_u32 s5, s73, 0
	global_load_dwordx4 v[190:193], v232, s[4:5] nt
	s_add_u32 s4, s70, 0x6000
	s_addc_u32 s5, s71, 0
	global_load_dwordx4 v[162:165], v232, s[4:5] nt
	s_add_u32 s4, s72, 0x6000
	s_addc_u32 s5, s73, 0
	global_load_dwordx4 v[194:197], v232, s[4:5] nt
	s_add_u32 s4, s70, 0x8000
	s_addc_u32 s5, s71, 0
	global_load_dwordx4 v[166:169], v232, s[4:5] nt
	s_add_u32 s4, s72, 0x8000
	s_addc_u32 s5, s73, 0
	global_load_dwordx4 v[198:201], v232, s[4:5] nt
	s_add_u32 s4, s70, 0xa000
	s_addc_u32 s5, s71, 0
	global_load_dwordx4 v[170:173], v232, s[4:5] nt
	s_add_u32 s4, s72, 0xa000
	s_addc_u32 s5, s73, 0
	global_load_dwordx4 v[202:205], v232, s[4:5] nt
	s_add_u32 s4, s70, 0xc000
	s_addc_u32 s5, s71, 0
	global_load_dwordx4 v[174:177], v232, s[4:5] nt
	s_add_u32 s4, s72, 0xc000
	s_addc_u32 s5, s73, 0
	global_load_dwordx4 v[206:209], v232, s[4:5] nt
	s_add_u32 s4, s70, 0xe000
	s_addc_u32 s5, s71, 0
	global_load_dwordx4 v[178:181], v232, s[4:5] nt
	s_add_u32 s4, s72, 0xe000
	s_addc_u32 s5, s73, 0
	global_load_dwordx4 v[210:213], v232, s[4:5] nt
	s_waitcnt vmcnt(14)
	v_lshlrev_b32_e32 v224, 16, v130
	v_and_b32_e32 v225, 0xffff0000, v130
	v_lshlrev_b32_e32 v228, 16, v182
	v_and_b32_e32 v229, 0xffff0000, v182
	v_pk_fma_f32 v[126:127], v[126:127], v[224:225], v[228:229]
	v_lshlrev_b32_e32 v226, 16, v131
	v_and_b32_e32 v227, 0xffff0000, v131
	v_lshlrev_b32_e32 v230, 16, v183
	v_and_b32_e32 v231, 0xffff0000, v183
	v_pk_fma_f32 v[128:129], v[128:129], v[226:227], v[230:231]
	v_lshlrev_b32_e32 v224, 16, v132
	v_and_b32_e32 v225, 0xffff0000, v132
	v_lshlrev_b32_e32 v228, 16, v184
	v_and_b32_e32 v229, 0xffff0000, v184
	v_pk_fma_f32 v[122:123], v[122:123], v[224:225], v[228:229]
	v_lshlrev_b32_e32 v226, 16, v133
	v_and_b32_e32 v227, 0xffff0000, v133
	v_lshlrev_b32_e32 v230, 16, v185
	v_and_b32_e32 v231, 0xffff0000, v185
	v_pk_fma_f32 v[124:125], v[124:125], v[226:227], v[230:231]
	v_cvt_pk_bf16_f32 v126, v126, v127
	v_cvt_pk_bf16_f32 v127, v128, v129
	v_cvt_pk_bf16_f32 v128, v122, v123
	v_cvt_pk_bf16_f32 v129, v124, v125
	s_add_u32 s76, s72, 0x0
	s_addc_u32 s77, s73, 0
	global_store_dwordx4 v232, v[126:129], s[76:77] nt
	s_add_u32 s4, s70, 0x10000
	s_addc_u32 s5, s71, 0
	global_load_dwordx4 v[130:133], v232, s[4:5] nt
	s_add_u32 s4, s72, 0x10000
	s_addc_u32 s5, s73, 0
	global_load_dwordx4 v[182:185], v232, s[4:5] nt
	s_waitcnt vmcnt(15)
	v_lshlrev_b32_e32 v224, 16, v134
	v_and_b32_e32 v225, 0xffff0000, v134
	v_lshlrev_b32_e32 v228, 16, v186
	v_and_b32_e32 v229, 0xffff0000, v186
	v_pk_fma_f32 v[118:119], v[118:119], v[224:225], v[228:229]
	v_lshlrev_b32_e32 v226, 16, v135
	v_and_b32_e32 v227, 0xffff0000, v135
	v_lshlrev_b32_e32 v230, 16, v187
	v_and_b32_e32 v231, 0xffff0000, v187
	v_pk_fma_f32 v[120:121], v[120:121], v[226:227], v[230:231]
	v_lshlrev_b32_e32 v224, 16, v136
	v_and_b32_e32 v225, 0xffff0000, v136
	v_lshlrev_b32_e32 v228, 16, v188
	v_and_b32_e32 v229, 0xffff0000, v188
	v_pk_fma_f32 v[114:115], v[114:115], v[224:225], v[228:229]
	v_lshlrev_b32_e32 v226, 16, v137
	v_and_b32_e32 v227, 0xffff0000, v137
	v_lshlrev_b32_e32 v230, 16, v189
	v_and_b32_e32 v231, 0xffff0000, v189
	v_pk_fma_f32 v[116:117], v[116:117], v[226:227], v[230:231]
	v_cvt_pk_bf16_f32 v118, v118, v119
	v_cvt_pk_bf16_f32 v119, v120, v121
	v_cvt_pk_bf16_f32 v120, v114, v115
	v_cvt_pk_bf16_f32 v121, v116, v117
	s_add_u32 s76, s72, 0x2000
	s_addc_u32 s77, s73, 0
	global_store_dwordx4 v232, v[118:121], s[76:77] nt
	s_add_u32 s4, s70, 0x12000
	s_addc_u32 s5, s71, 0
	global_load_dwordx4 v[134:137], v232, s[4:5] nt
	s_add_u32 s4, s72, 0x12000
	s_addc_u32 s5, s73, 0
	global_load_dwordx4 v[186:189], v232, s[4:5] nt
	s_waitcnt vmcnt(16)
	v_lshlrev_b32_e32 v224, 16, v156
	v_and_b32_e32 v225, 0xffff0000, v156
	v_lshlrev_b32_e32 v228, 16, v190
	v_and_b32_e32 v229, 0xffff0000, v190
	v_pk_fma_f32 v[110:111], v[110:111], v[224:225], v[228:229]
	v_lshlrev_b32_e32 v226, 16, v157
	v_and_b32_e32 v227, 0xffff0000, v157
	v_lshlrev_b32_e32 v230, 16, v191
	v_and_b32_e32 v231, 0xffff0000, v191
	v_pk_fma_f32 v[112:113], v[112:113], v[226:227], v[230:231]
	v_lshlrev_b32_e32 v224, 16, v158
	v_and_b32_e32 v225, 0xffff0000, v158
	v_lshlrev_b32_e32 v228, 16, v192
	v_and_b32_e32 v229, 0xffff0000, v192
	v_pk_fma_f32 v[106:107], v[106:107], v[224:225], v[228:229]
	v_lshlrev_b32_e32 v226, 16, v159
	v_and_b32_e32 v227, 0xffff0000, v159
	v_lshlrev_b32_e32 v230, 16, v193
	v_and_b32_e32 v231, 0xffff0000, v193
	v_pk_fma_f32 v[108:109], v[108:109], v[226:227], v[230:231]
	v_cvt_pk_bf16_f32 v110, v110, v111
	v_cvt_pk_bf16_f32 v111, v112, v113
	v_cvt_pk_bf16_f32 v112, v106, v107
	v_cvt_pk_bf16_f32 v113, v108, v109
	s_add_u32 s76, s72, 0x4000
	s_addc_u32 s77, s73, 0
	global_store_dwordx4 v232, v[110:113], s[76:77] nt
	s_add_u32 s4, s70, 0x14000
	s_addc_u32 s5, s71, 0
	global_load_dwordx4 v[156:159], v232, s[4:5] nt
	s_add_u32 s4, s72, 0x14000
	s_addc_u32 s5, s73, 0
	global_load_dwordx4 v[190:193], v232, s[4:5] nt
	s_waitcnt vmcnt(17)
	v_lshlrev_b32_e32 v224, 16, v162
	v_and_b32_e32 v225, 0xffff0000, v162
	v_lshlrev_b32_e32 v228, 16, v194
	v_and_b32_e32 v229, 0xffff0000, v194
	v_pk_fma_f32 v[102:103], v[102:103], v[224:225], v[228:229]
	v_lshlrev_b32_e32 v226, 16, v163
	v_and_b32_e32 v227, 0xffff0000, v163
	v_lshlrev_b32_e32 v230, 16, v195
	v_and_b32_e32 v231, 0xffff0000, v195
	v_pk_fma_f32 v[104:105], v[104:105], v[226:227], v[230:231]
	v_lshlrev_b32_e32 v224, 16, v164
	v_and_b32_e32 v225, 0xffff0000, v164
	v_lshlrev_b32_e32 v228, 16, v196
	v_and_b32_e32 v229, 0xffff0000, v196
	v_pk_fma_f32 v[98:99], v[98:99], v[224:225], v[228:229]
	v_lshlrev_b32_e32 v226, 16, v165
	v_and_b32_e32 v227, 0xffff0000, v165
	v_lshlrev_b32_e32 v230, 16, v197
	v_and_b32_e32 v231, 0xffff0000, v197
	v_pk_fma_f32 v[100:101], v[100:101], v[226:227], v[230:231]
	v_cvt_pk_bf16_f32 v102, v102, v103
	v_cvt_pk_bf16_f32 v103, v104, v105
	v_cvt_pk_bf16_f32 v104, v98, v99
	v_cvt_pk_bf16_f32 v105, v100, v101
	s_add_u32 s76, s72, 0x6000
	s_addc_u32 s77, s73, 0
	global_store_dwordx4 v232, v[102:105], s[76:77] nt
	s_add_u32 s4, s70, 0x16000
	s_addc_u32 s5, s71, 0
	global_load_dwordx4 v[162:165], v232, s[4:5] nt
	s_add_u32 s4, s72, 0x16000
	s_addc_u32 s5, s73, 0
	global_load_dwordx4 v[194:197], v232, s[4:5] nt
	s_waitcnt vmcnt(18)
	v_lshlrev_b32_e32 v224, 16, v166
	v_and_b32_e32 v225, 0xffff0000, v166
	v_lshlrev_b32_e32 v228, 16, v198
	v_and_b32_e32 v229, 0xffff0000, v198
	v_pk_fma_f32 v[94:95], v[94:95], v[224:225], v[228:229]
	v_lshlrev_b32_e32 v226, 16, v167
	v_and_b32_e32 v227, 0xffff0000, v167
	v_lshlrev_b32_e32 v230, 16, v199
	v_and_b32_e32 v231, 0xffff0000, v199
	v_pk_fma_f32 v[96:97], v[96:97], v[226:227], v[230:231]
	v_lshlrev_b32_e32 v224, 16, v168
	v_and_b32_e32 v225, 0xffff0000, v168
	v_lshlrev_b32_e32 v228, 16, v200
	v_and_b32_e32 v229, 0xffff0000, v200
	v_pk_fma_f32 v[90:91], v[90:91], v[224:225], v[228:229]
	v_lshlrev_b32_e32 v226, 16, v169
	v_and_b32_e32 v227, 0xffff0000, v169
	v_lshlrev_b32_e32 v230, 16, v201
	v_and_b32_e32 v231, 0xffff0000, v201
	v_pk_fma_f32 v[92:93], v[92:93], v[226:227], v[230:231]
	v_cvt_pk_bf16_f32 v94, v94, v95
	v_cvt_pk_bf16_f32 v95, v96, v97
	v_cvt_pk_bf16_f32 v96, v90, v91
	v_cvt_pk_bf16_f32 v97, v92, v93
	s_add_u32 s76, s72, 0x8000
	s_addc_u32 s77, s73, 0
	global_store_dwordx4 v232, v[94:97], s[76:77] nt
	s_add_u32 s4, s70, 0x18000
	s_addc_u32 s5, s71, 0
	global_load_dwordx4 v[166:169], v232, s[4:5] nt
	s_add_u32 s4, s72, 0x18000
	s_addc_u32 s5, s73, 0
	global_load_dwordx4 v[198:201], v232, s[4:5] nt
	s_waitcnt vmcnt(19)
	v_lshlrev_b32_e32 v224, 16, v170
	v_and_b32_e32 v225, 0xffff0000, v170
	v_lshlrev_b32_e32 v228, 16, v202
	v_and_b32_e32 v229, 0xffff0000, v202
	v_pk_fma_f32 v[86:87], v[86:87], v[224:225], v[228:229]
	v_lshlrev_b32_e32 v226, 16, v171
	v_and_b32_e32 v227, 0xffff0000, v171
	v_lshlrev_b32_e32 v230, 16, v203
	v_and_b32_e32 v231, 0xffff0000, v203
	v_pk_fma_f32 v[88:89], v[88:89], v[226:227], v[230:231]
	v_lshlrev_b32_e32 v224, 16, v172
	v_and_b32_e32 v225, 0xffff0000, v172
	v_lshlrev_b32_e32 v228, 16, v204
	v_and_b32_e32 v229, 0xffff0000, v204
	v_pk_fma_f32 v[82:83], v[82:83], v[224:225], v[228:229]
	v_lshlrev_b32_e32 v226, 16, v173
	v_and_b32_e32 v227, 0xffff0000, v173
	v_lshlrev_b32_e32 v230, 16, v205
	v_and_b32_e32 v231, 0xffff0000, v205
	v_pk_fma_f32 v[84:85], v[84:85], v[226:227], v[230:231]
	v_cvt_pk_bf16_f32 v86, v86, v87
	v_cvt_pk_bf16_f32 v87, v88, v89
	v_cvt_pk_bf16_f32 v88, v82, v83
	v_cvt_pk_bf16_f32 v89, v84, v85
	s_add_u32 s76, s72, 0xa000
	s_addc_u32 s77, s73, 0
	global_store_dwordx4 v232, v[86:89], s[76:77] nt
	s_add_u32 s4, s70, 0x1a000
	s_addc_u32 s5, s71, 0
	global_load_dwordx4 v[170:173], v232, s[4:5] nt
	s_add_u32 s4, s72, 0x1a000
	s_addc_u32 s5, s73, 0
	global_load_dwordx4 v[202:205], v232, s[4:5] nt
	s_waitcnt vmcnt(20)
	v_lshlrev_b32_e32 v224, 16, v174
	v_and_b32_e32 v225, 0xffff0000, v174
	v_lshlrev_b32_e32 v228, 16, v206
	v_and_b32_e32 v229, 0xffff0000, v206
	v_pk_fma_f32 v[78:79], v[78:79], v[224:225], v[228:229]
	v_lshlrev_b32_e32 v226, 16, v175
	v_and_b32_e32 v227, 0xffff0000, v175
	v_lshlrev_b32_e32 v230, 16, v207
	v_and_b32_e32 v231, 0xffff0000, v207
	v_pk_fma_f32 v[80:81], v[80:81], v[226:227], v[230:231]
	v_lshlrev_b32_e32 v224, 16, v176
	v_and_b32_e32 v225, 0xffff0000, v176
	v_lshlrev_b32_e32 v228, 16, v208
	v_and_b32_e32 v229, 0xffff0000, v208
	v_pk_fma_f32 v[74:75], v[74:75], v[224:225], v[228:229]
	v_lshlrev_b32_e32 v226, 16, v177
	v_and_b32_e32 v227, 0xffff0000, v177
	v_lshlrev_b32_e32 v230, 16, v209
	v_and_b32_e32 v231, 0xffff0000, v209
	v_pk_fma_f32 v[76:77], v[76:77], v[226:227], v[230:231]
	v_cvt_pk_bf16_f32 v78, v78, v79
	v_cvt_pk_bf16_f32 v79, v80, v81
	v_cvt_pk_bf16_f32 v80, v74, v75
	v_cvt_pk_bf16_f32 v81, v76, v77
	s_add_u32 s76, s72, 0xc000
	s_addc_u32 s77, s73, 0
	global_store_dwordx4 v232, v[78:81], s[76:77] nt
	s_add_u32 s4, s70, 0x1c000
	s_addc_u32 s5, s71, 0
	global_load_dwordx4 v[174:177], v232, s[4:5] nt
	s_add_u32 s4, s72, 0x1c000
	s_addc_u32 s5, s73, 0
	global_load_dwordx4 v[206:209], v232, s[4:5] nt
	s_waitcnt vmcnt(21)
	v_lshlrev_b32_e32 v224, 16, v178
	v_and_b32_e32 v225, 0xffff0000, v178
	v_lshlrev_b32_e32 v228, 16, v210
	v_and_b32_e32 v229, 0xffff0000, v210
	v_pk_fma_f32 v[70:71], v[70:71], v[224:225], v[228:229]
	v_lshlrev_b32_e32 v226, 16, v179
	v_and_b32_e32 v227, 0xffff0000, v179
	v_lshlrev_b32_e32 v230, 16, v211
	v_and_b32_e32 v231, 0xffff0000, v211
	v_pk_fma_f32 v[72:73], v[72:73], v[226:227], v[230:231]
	v_lshlrev_b32_e32 v224, 16, v180
	v_and_b32_e32 v225, 0xffff0000, v180
	v_lshlrev_b32_e32 v228, 16, v212
	v_and_b32_e32 v229, 0xffff0000, v212
	v_pk_fma_f32 v[66:67], v[66:67], v[224:225], v[228:229]
	v_lshlrev_b32_e32 v226, 16, v181
	v_and_b32_e32 v227, 0xffff0000, v181
	v_lshlrev_b32_e32 v230, 16, v213
	v_and_b32_e32 v231, 0xffff0000, v213
	v_pk_fma_f32 v[68:69], v[68:69], v[226:227], v[230:231]
	v_cvt_pk_bf16_f32 v70, v70, v71
	v_cvt_pk_bf16_f32 v71, v72, v73
	v_cvt_pk_bf16_f32 v72, v66, v67
	v_cvt_pk_bf16_f32 v73, v68, v69
	s_add_u32 s76, s72, 0xe000
	s_addc_u32 s77, s73, 0
	global_store_dwordx4 v232, v[70:73], s[76:77] nt
	s_add_u32 s4, s70, 0x1e000
	s_addc_u32 s5, s71, 0
	global_load_dwordx4 v[178:181], v232, s[4:5] nt
	s_add_u32 s4, s72, 0x1e000
	s_addc_u32 s5, s73, 0
	global_load_dwordx4 v[210:213], v232, s[4:5] nt
	s_waitcnt vmcnt(21)
	v_lshlrev_b32_e32 v224, 16, v130
	v_and_b32_e32 v225, 0xffff0000, v130
	v_lshlrev_b32_e32 v228, 16, v182
	v_and_b32_e32 v229, 0xffff0000, v182
	v_pk_fma_f32 v[62:63], v[62:63], v[224:225], v[228:229]
	v_lshlrev_b32_e32 v226, 16, v131
	v_and_b32_e32 v227, 0xffff0000, v131
	v_lshlrev_b32_e32 v230, 16, v183
	v_and_b32_e32 v231, 0xffff0000, v183
	v_pk_fma_f32 v[64:65], v[64:65], v[226:227], v[230:231]
	v_lshlrev_b32_e32 v224, 16, v132
	v_and_b32_e32 v225, 0xffff0000, v132
	v_lshlrev_b32_e32 v228, 16, v184
	v_and_b32_e32 v229, 0xffff0000, v184
	v_pk_fma_f32 v[58:59], v[58:59], v[224:225], v[228:229]
	v_lshlrev_b32_e32 v226, 16, v133
	v_and_b32_e32 v227, 0xffff0000, v133
	v_lshlrev_b32_e32 v230, 16, v185
	v_and_b32_e32 v231, 0xffff0000, v185
	v_pk_fma_f32 v[60:61], v[60:61], v[226:227], v[230:231]
	v_cvt_pk_bf16_f32 v62, v62, v63
	v_cvt_pk_bf16_f32 v63, v64, v65
	v_cvt_pk_bf16_f32 v64, v58, v59
	v_cvt_pk_bf16_f32 v65, v60, v61
	s_add_u32 s76, s72, 0x10000
	s_addc_u32 s77, s73, 0
	global_store_dwordx4 v232, v[62:65], s[76:77] nt
	s_waitcnt vmcnt(19)
	v_lshlrev_b32_e32 v224, 16, v134
	v_and_b32_e32 v225, 0xffff0000, v134
	v_lshlrev_b32_e32 v228, 16, v186
	v_and_b32_e32 v229, 0xffff0000, v186
	v_pk_fma_f32 v[54:55], v[54:55], v[224:225], v[228:229]
	v_lshlrev_b32_e32 v226, 16, v135
	v_and_b32_e32 v227, 0xffff0000, v135
	v_lshlrev_b32_e32 v230, 16, v187
	v_and_b32_e32 v231, 0xffff0000, v187
	v_pk_fma_f32 v[56:57], v[56:57], v[226:227], v[230:231]
	v_lshlrev_b32_e32 v224, 16, v136
	v_and_b32_e32 v225, 0xffff0000, v136
	v_lshlrev_b32_e32 v228, 16, v188
	v_and_b32_e32 v229, 0xffff0000, v188
	v_pk_fma_f32 v[50:51], v[50:51], v[224:225], v[228:229]
	v_lshlrev_b32_e32 v226, 16, v137
	v_and_b32_e32 v227, 0xffff0000, v137
	v_lshlrev_b32_e32 v230, 16, v189
	v_and_b32_e32 v231, 0xffff0000, v189
	v_pk_fma_f32 v[52:53], v[52:53], v[226:227], v[230:231]
	v_cvt_pk_bf16_f32 v54, v54, v55
	v_cvt_pk_bf16_f32 v55, v56, v57
	v_cvt_pk_bf16_f32 v56, v50, v51
	v_cvt_pk_bf16_f32 v57, v52, v53
	s_add_u32 s76, s72, 0x12000
	s_addc_u32 s77, s73, 0
	global_store_dwordx4 v232, v[54:57], s[76:77] nt
	s_waitcnt vmcnt(17)
	v_lshlrev_b32_e32 v224, 16, v156
	v_and_b32_e32 v225, 0xffff0000, v156
	v_lshlrev_b32_e32 v228, 16, v190
	v_and_b32_e32 v229, 0xffff0000, v190
	v_pk_fma_f32 v[46:47], v[46:47], v[224:225], v[228:229]
	v_lshlrev_b32_e32 v226, 16, v157
	v_and_b32_e32 v227, 0xffff0000, v157
	v_lshlrev_b32_e32 v230, 16, v191
	v_and_b32_e32 v231, 0xffff0000, v191
	v_pk_fma_f32 v[48:49], v[48:49], v[226:227], v[230:231]
	v_lshlrev_b32_e32 v224, 16, v158
	v_and_b32_e32 v225, 0xffff0000, v158
	v_lshlrev_b32_e32 v228, 16, v192
	v_and_b32_e32 v229, 0xffff0000, v192
	v_pk_fma_f32 v[42:43], v[42:43], v[224:225], v[228:229]
	v_lshlrev_b32_e32 v226, 16, v159
	v_and_b32_e32 v227, 0xffff0000, v159
	v_lshlrev_b32_e32 v230, 16, v193
	v_and_b32_e32 v231, 0xffff0000, v193
	v_pk_fma_f32 v[44:45], v[44:45], v[226:227], v[230:231]
	v_cvt_pk_bf16_f32 v46, v46, v47
	v_cvt_pk_bf16_f32 v47, v48, v49
	v_cvt_pk_bf16_f32 v48, v42, v43
	v_cvt_pk_bf16_f32 v49, v44, v45
	s_add_u32 s76, s72, 0x14000
	s_addc_u32 s77, s73, 0
	global_store_dwordx4 v232, v[46:49], s[76:77] nt
	s_waitcnt vmcnt(15)
	v_lshlrev_b32_e32 v224, 16, v162
	v_and_b32_e32 v225, 0xffff0000, v162
	v_lshlrev_b32_e32 v228, 16, v194
	v_and_b32_e32 v229, 0xffff0000, v194
	v_pk_fma_f32 v[38:39], v[38:39], v[224:225], v[228:229]
	v_lshlrev_b32_e32 v226, 16, v163
	v_and_b32_e32 v227, 0xffff0000, v163
	v_lshlrev_b32_e32 v230, 16, v195
	v_and_b32_e32 v231, 0xffff0000, v195
	v_pk_fma_f32 v[40:41], v[40:41], v[226:227], v[230:231]
	v_lshlrev_b32_e32 v224, 16, v164
	v_and_b32_e32 v225, 0xffff0000, v164
	v_lshlrev_b32_e32 v228, 16, v196
	v_and_b32_e32 v229, 0xffff0000, v196
	v_pk_fma_f32 v[34:35], v[34:35], v[224:225], v[228:229]
	v_lshlrev_b32_e32 v226, 16, v165
	v_and_b32_e32 v227, 0xffff0000, v165
	v_lshlrev_b32_e32 v230, 16, v197
	v_and_b32_e32 v231, 0xffff0000, v197
	v_pk_fma_f32 v[36:37], v[36:37], v[226:227], v[230:231]
	v_cvt_pk_bf16_f32 v38, v38, v39
	v_cvt_pk_bf16_f32 v39, v40, v41
	v_cvt_pk_bf16_f32 v40, v34, v35
	v_cvt_pk_bf16_f32 v41, v36, v37
	s_add_u32 s76, s72, 0x16000
	s_addc_u32 s77, s73, 0
	global_store_dwordx4 v232, v[38:41], s[76:77] nt
	s_waitcnt vmcnt(13)
	v_lshlrev_b32_e32 v224, 16, v166
	v_and_b32_e32 v225, 0xffff0000, v166
	v_lshlrev_b32_e32 v228, 16, v198
	v_and_b32_e32 v229, 0xffff0000, v198
	v_pk_fma_f32 v[30:31], v[30:31], v[224:225], v[228:229]
	v_lshlrev_b32_e32 v226, 16, v167
	v_and_b32_e32 v227, 0xffff0000, v167
	v_lshlrev_b32_e32 v230, 16, v199
	v_and_b32_e32 v231, 0xffff0000, v199
	v_pk_fma_f32 v[32:33], v[32:33], v[226:227], v[230:231]
	v_lshlrev_b32_e32 v224, 16, v168
	v_and_b32_e32 v225, 0xffff0000, v168
	v_lshlrev_b32_e32 v228, 16, v200
	v_and_b32_e32 v229, 0xffff0000, v200
	v_pk_fma_f32 v[26:27], v[26:27], v[224:225], v[228:229]
	v_lshlrev_b32_e32 v226, 16, v169
	v_and_b32_e32 v227, 0xffff0000, v169
	v_lshlrev_b32_e32 v230, 16, v201
	v_and_b32_e32 v231, 0xffff0000, v201
	v_pk_fma_f32 v[28:29], v[28:29], v[226:227], v[230:231]
	v_cvt_pk_bf16_f32 v30, v30, v31
	v_cvt_pk_bf16_f32 v31, v32, v33
	v_cvt_pk_bf16_f32 v32, v26, v27
	v_cvt_pk_bf16_f32 v33, v28, v29
	s_add_u32 s76, s72, 0x18000
	s_addc_u32 s77, s73, 0
	global_store_dwordx4 v232, v[30:33], s[76:77] nt
	s_waitcnt vmcnt(11)
	v_lshlrev_b32_e32 v224, 16, v170
	v_and_b32_e32 v225, 0xffff0000, v170
	v_lshlrev_b32_e32 v228, 16, v202
	v_and_b32_e32 v229, 0xffff0000, v202
	v_pk_fma_f32 v[22:23], v[22:23], v[224:225], v[228:229]
	v_lshlrev_b32_e32 v226, 16, v171
	v_and_b32_e32 v227, 0xffff0000, v171
	v_lshlrev_b32_e32 v230, 16, v203
	v_and_b32_e32 v231, 0xffff0000, v203
	v_pk_fma_f32 v[24:25], v[24:25], v[226:227], v[230:231]
	v_lshlrev_b32_e32 v224, 16, v172
	v_and_b32_e32 v225, 0xffff0000, v172
	v_lshlrev_b32_e32 v228, 16, v204
	v_and_b32_e32 v229, 0xffff0000, v204
	v_pk_fma_f32 v[18:19], v[18:19], v[224:225], v[228:229]
	v_lshlrev_b32_e32 v226, 16, v173
	v_and_b32_e32 v227, 0xffff0000, v173
	v_lshlrev_b32_e32 v230, 16, v205
	v_and_b32_e32 v231, 0xffff0000, v205
	v_pk_fma_f32 v[20:21], v[20:21], v[226:227], v[230:231]
	v_cvt_pk_bf16_f32 v22, v22, v23
	v_cvt_pk_bf16_f32 v23, v24, v25
	v_cvt_pk_bf16_f32 v24, v18, v19
	v_cvt_pk_bf16_f32 v25, v20, v21
	s_add_u32 s76, s72, 0x1a000
	s_addc_u32 s77, s73, 0
	global_store_dwordx4 v232, v[22:25], s[76:77] nt
	s_waitcnt vmcnt(9)
	v_lshlrev_b32_e32 v224, 16, v174
	v_and_b32_e32 v225, 0xffff0000, v174
	v_lshlrev_b32_e32 v228, 16, v206
	v_and_b32_e32 v229, 0xffff0000, v206
	v_pk_fma_f32 v[14:15], v[14:15], v[224:225], v[228:229]
	v_lshlrev_b32_e32 v226, 16, v175
	v_and_b32_e32 v227, 0xffff0000, v175
	v_lshlrev_b32_e32 v230, 16, v207
	v_and_b32_e32 v231, 0xffff0000, v207
	v_pk_fma_f32 v[16:17], v[16:17], v[226:227], v[230:231]
	v_lshlrev_b32_e32 v224, 16, v176
	v_and_b32_e32 v225, 0xffff0000, v176
	v_lshlrev_b32_e32 v228, 16, v208
	v_and_b32_e32 v229, 0xffff0000, v208
	v_pk_fma_f32 v[10:11], v[10:11], v[224:225], v[228:229]
	v_lshlrev_b32_e32 v226, 16, v177
	v_and_b32_e32 v227, 0xffff0000, v177
	v_lshlrev_b32_e32 v230, 16, v209
	v_and_b32_e32 v231, 0xffff0000, v209
	v_pk_fma_f32 v[12:13], v[12:13], v[226:227], v[230:231]
	v_cvt_pk_bf16_f32 v14, v14, v15
	v_cvt_pk_bf16_f32 v15, v16, v17
	v_cvt_pk_bf16_f32 v16, v10, v11
	v_cvt_pk_bf16_f32 v17, v12, v13
	s_add_u32 s76, s72, 0x1c000
	s_addc_u32 s77, s73, 0
	global_store_dwordx4 v232, v[14:17], s[76:77] nt
	s_waitcnt vmcnt(7)
	v_lshlrev_b32_e32 v224, 16, v178
	v_and_b32_e32 v225, 0xffff0000, v178
	v_lshlrev_b32_e32 v228, 16, v210
	v_and_b32_e32 v229, 0xffff0000, v210
	v_pk_fma_f32 v[6:7], v[6:7], v[224:225], v[228:229]
	v_lshlrev_b32_e32 v226, 16, v179
	v_and_b32_e32 v227, 0xffff0000, v179
	v_lshlrev_b32_e32 v230, 16, v211
	v_and_b32_e32 v231, 0xffff0000, v211
	v_pk_fma_f32 v[8:9], v[8:9], v[226:227], v[230:231]
	v_lshlrev_b32_e32 v224, 16, v180
	v_and_b32_e32 v225, 0xffff0000, v180
	v_lshlrev_b32_e32 v228, 16, v212
	v_and_b32_e32 v229, 0xffff0000, v212
	v_pk_fma_f32 v[0:1], v[0:1], v[224:225], v[228:229]
	v_lshlrev_b32_e32 v226, 16, v181
	v_and_b32_e32 v227, 0xffff0000, v181
	v_lshlrev_b32_e32 v230, 16, v213
	v_and_b32_e32 v231, 0xffff0000, v213
	v_pk_fma_f32 v[2:3], v[2:3], v[226:227], v[230:231]
	v_cvt_pk_bf16_f32 v6, v6, v7
	v_cvt_pk_bf16_f32 v7, v8, v9
	v_cvt_pk_bf16_f32 v8, v0, v1
	v_cvt_pk_bf16_f32 v9, v2, v3
	s_add_u32 s76, s72, 0x1e000
	s_addc_u32 s77, s73, 0
	global_store_dwordx4 v232, v[6:9], s[76:77] nt
	s_branch .Lmrg_done
.Lmrg_seg2:
	s_add_u32 s70, s26, s93
	s_addc_u32 s71, s27, 0
	s_add_u32 s70, s70, s4
	s_addc_u32 s71, s71, 0
	s_lshl_b32 s5, s8, 19
	s_lshl_b32 s76, s6, 9
	s_add_u32 s5, s5, s76
	s_add_u32 s74, s24, s5
	s_addc_u32 s75, s25, 0
	v_add_u32_e32 v233, s45, v5
	v_lshlrev_b32_e32 v233, 11, v233
	v_lshl_add_u32 v234, v139, 3, s51
	v_lshl_add_u32 v233, v234, 1, v233
	s_add_u32 s4, s70, 0x0
	s_addc_u32 s5, s71, 0
	global_load_dwordx4 v[130:133], v232, s[4:5] nt
	s_add_u32 s4, s72, 0x0
	s_addc_u32 s5, s73, 0
	global_load_dwordx4 v[182:185], v232, s[4:5] nt
	s_add_u32 s4, s70, 0x2000
	s_addc_u32 s5, s71, 0
	global_load_dwordx4 v[134:137], v232, s[4:5] nt
	s_add_u32 s4, s72, 0x2000
	s_addc_u32 s5, s73, 0
	global_load_dwordx4 v[186:189], v232, s[4:5] nt
	s_add_u32 s4, s70, 0x4000
	s_addc_u32 s5, s71, 0
	global_load_dwordx4 v[156:159], v232, s[4:5] nt
	s_add_u32 s4, s72, 0x4000
	s_addc_u32 s5, s73, 0
	global_load_dwordx4 v[190:193], v232, s[4:5] nt
	s_add_u32 s4, s70, 0x6000
	s_addc_u32 s5, s71, 0
	global_load_dwordx4 v[162:165], v232, s[4:5] nt
	s_add_u32 s4, s72, 0x6000
	s_addc_u32 s5, s73, 0
	global_load_dwordx4 v[194:197], v232, s[4:5] nt
	s_add_u32 s4, s70, 0x8000
	s_addc_u32 s5, s71, 0
	global_load_dwordx4 v[166:169], v232, s[4:5] nt
	s_add_u32 s4, s72, 0x8000
	s_addc_u32 s5, s73, 0
	global_load_dwordx4 v[198:201], v232, s[4:5] nt
	s_add_u32 s4, s70, 0xa000
	s_addc_u32 s5, s71, 0
	global_load_dwordx4 v[170:173], v232, s[4:5] nt
	s_add_u32 s4, s72, 0xa000
	s_addc_u32 s5, s73, 0
	global_load_dwordx4 v[202:205], v232, s[4:5] nt
	s_add_u32 s4, s70, 0xc000
	s_addc_u32 s5, s71, 0
	global_load_dwordx4 v[174:177], v232, s[4:5] nt
	s_add_u32 s4, s72, 0xc000
	s_addc_u32 s5, s73, 0
	global_load_dwordx4 v[206:209], v232, s[4:5] nt
	s_add_u32 s4, s70, 0xe000
	s_addc_u32 s5, s71, 0
	global_load_dwordx4 v[178:181], v232, s[4:5] nt
	s_add_u32 s4, s72, 0xe000
	s_addc_u32 s5, s73, 0
	global_load_dwordx4 v[210:213], v232, s[4:5] nt
	s_waitcnt vmcnt(14)
	v_lshlrev_b32_e32 v224, 16, v130
	v_and_b32_e32 v225, 0xffff0000, v130
	v_lshlrev_b32_e32 v228, 16, v182
	v_and_b32_e32 v229, 0xffff0000, v182
	v_pk_fma_f32 v[126:127], v[126:127], v[224:225], v[228:229]
	v_lshlrev_b32_e32 v226, 16, v131
	v_and_b32_e32 v227, 0xffff0000, v131
	v_lshlrev_b32_e32 v230, 16, v183
	v_and_b32_e32 v231, 0xffff0000, v183
	v_pk_fma_f32 v[128:129], v[128:129], v[226:227], v[230:231]
	v_lshlrev_b32_e32 v224, 16, v132
	v_and_b32_e32 v225, 0xffff0000, v132
	v_lshlrev_b32_e32 v228, 16, v184
	v_and_b32_e32 v229, 0xffff0000, v184
	v_pk_fma_f32 v[122:123], v[122:123], v[224:225], v[228:229]
	v_lshlrev_b32_e32 v226, 16, v133
	v_and_b32_e32 v227, 0xffff0000, v133
	v_lshlrev_b32_e32 v230, 16, v185
	v_and_b32_e32 v231, 0xffff0000, v185
	v_pk_fma_f32 v[124:125], v[124:125], v[226:227], v[230:231]
	v_cvt_pk_bf16_f32 v126, v126, v127
	v_cvt_pk_bf16_f32 v127, v128, v129
	v_cvt_pk_bf16_f32 v128, v122, v123
	v_cvt_pk_bf16_f32 v129, v124, v125
	s_add_u32 s76, s74, 0x0
	s_addc_u32 s77, s75, 0
	global_store_dwordx4 v233, v[126:129], s[76:77]
	s_add_u32 s4, s70, 0x10000
	s_addc_u32 s5, s71, 0
	global_load_dwordx4 v[130:133], v232, s[4:5] nt
	s_add_u32 s4, s72, 0x10000
	s_addc_u32 s5, s73, 0
	global_load_dwordx4 v[182:185], v232, s[4:5] nt
	s_waitcnt vmcnt(15)
	v_lshlrev_b32_e32 v224, 16, v134
	v_and_b32_e32 v225, 0xffff0000, v134
	v_lshlrev_b32_e32 v228, 16, v186
	v_and_b32_e32 v229, 0xffff0000, v186
	v_pk_fma_f32 v[118:119], v[118:119], v[224:225], v[228:229]
	v_lshlrev_b32_e32 v226, 16, v135
	v_and_b32_e32 v227, 0xffff0000, v135
	v_lshlrev_b32_e32 v230, 16, v187
	v_and_b32_e32 v231, 0xffff0000, v187
	v_pk_fma_f32 v[120:121], v[120:121], v[226:227], v[230:231]
	v_lshlrev_b32_e32 v224, 16, v136
	v_and_b32_e32 v225, 0xffff0000, v136
	v_lshlrev_b32_e32 v228, 16, v188
	v_and_b32_e32 v229, 0xffff0000, v188
	v_pk_fma_f32 v[114:115], v[114:115], v[224:225], v[228:229]
	v_lshlrev_b32_e32 v226, 16, v137
	v_and_b32_e32 v227, 0xffff0000, v137
	v_lshlrev_b32_e32 v230, 16, v189
	v_and_b32_e32 v231, 0xffff0000, v189
	v_pk_fma_f32 v[116:117], v[116:117], v[226:227], v[230:231]
	v_cvt_pk_bf16_f32 v118, v118, v119
	v_cvt_pk_bf16_f32 v119, v120, v121
	v_cvt_pk_bf16_f32 v120, v114, v115
	v_cvt_pk_bf16_f32 v121, v116, v117
	s_add_u32 s76, s74, 0x8000
	s_addc_u32 s77, s75, 0
	global_store_dwordx4 v233, v[118:121], s[76:77]
	s_add_u32 s4, s70, 0x12000
	s_addc_u32 s5, s71, 0
	global_load_dwordx4 v[134:137], v232, s[4:5] nt
	s_add_u32 s4, s72, 0x12000
	s_addc_u32 s5, s73, 0
	global_load_dwordx4 v[186:189], v232, s[4:5] nt
	s_waitcnt vmcnt(16)
	v_lshlrev_b32_e32 v224, 16, v156
	v_and_b32_e32 v225, 0xffff0000, v156
	v_lshlrev_b32_e32 v228, 16, v190
	v_and_b32_e32 v229, 0xffff0000, v190
	v_pk_fma_f32 v[110:111], v[110:111], v[224:225], v[228:229]
	v_lshlrev_b32_e32 v226, 16, v157
	v_and_b32_e32 v227, 0xffff0000, v157
	v_lshlrev_b32_e32 v230, 16, v191
	v_and_b32_e32 v231, 0xffff0000, v191
	v_pk_fma_f32 v[112:113], v[112:113], v[226:227], v[230:231]
	v_lshlrev_b32_e32 v224, 16, v158
	v_and_b32_e32 v225, 0xffff0000, v158
	v_lshlrev_b32_e32 v228, 16, v192
	v_and_b32_e32 v229, 0xffff0000, v192
	v_pk_fma_f32 v[106:107], v[106:107], v[224:225], v[228:229]
	v_lshlrev_b32_e32 v226, 16, v159
	v_and_b32_e32 v227, 0xffff0000, v159
	v_lshlrev_b32_e32 v230, 16, v193
	v_and_b32_e32 v231, 0xffff0000, v193
	v_pk_fma_f32 v[108:109], v[108:109], v[226:227], v[230:231]
	v_cvt_pk_bf16_f32 v110, v110, v111
	v_cvt_pk_bf16_f32 v111, v112, v113
	v_cvt_pk_bf16_f32 v112, v106, v107
	v_cvt_pk_bf16_f32 v113, v108, v109
	s_add_u32 s76, s74, 0x10000
	s_addc_u32 s77, s75, 0
	global_store_dwordx4 v233, v[110:113], s[76:77]
	s_add_u32 s4, s70, 0x14000
	s_addc_u32 s5, s71, 0
	global_load_dwordx4 v[156:159], v232, s[4:5] nt
	s_add_u32 s4, s72, 0x14000
	s_addc_u32 s5, s73, 0
	global_load_dwordx4 v[190:193], v232, s[4:5] nt
	s_waitcnt vmcnt(17)
	v_lshlrev_b32_e32 v224, 16, v162
	v_and_b32_e32 v225, 0xffff0000, v162
	v_lshlrev_b32_e32 v228, 16, v194
	v_and_b32_e32 v229, 0xffff0000, v194
	v_pk_fma_f32 v[102:103], v[102:103], v[224:225], v[228:229]
	v_lshlrev_b32_e32 v226, 16, v163
	v_and_b32_e32 v227, 0xffff0000, v163
	v_lshlrev_b32_e32 v230, 16, v195
	v_and_b32_e32 v231, 0xffff0000, v195
	v_pk_fma_f32 v[104:105], v[104:105], v[226:227], v[230:231]
	v_lshlrev_b32_e32 v224, 16, v164
	v_and_b32_e32 v225, 0xffff0000, v164
	v_lshlrev_b32_e32 v228, 16, v196
	v_and_b32_e32 v229, 0xffff0000, v196
	v_pk_fma_f32 v[98:99], v[98:99], v[224:225], v[228:229]
	v_lshlrev_b32_e32 v226, 16, v165
	v_and_b32_e32 v227, 0xffff0000, v165
	v_lshlrev_b32_e32 v230, 16, v197
	v_and_b32_e32 v231, 0xffff0000, v197
	v_pk_fma_f32 v[100:101], v[100:101], v[226:227], v[230:231]
	v_cvt_pk_bf16_f32 v102, v102, v103
	v_cvt_pk_bf16_f32 v103, v104, v105
	v_cvt_pk_bf16_f32 v104, v98, v99
	v_cvt_pk_bf16_f32 v105, v100, v101
	s_add_u32 s76, s74, 0x18000
	s_addc_u32 s77, s75, 0
	global_store_dwordx4 v233, v[102:105], s[76:77]
	s_add_u32 s4, s70, 0x16000
	s_addc_u32 s5, s71, 0
	global_load_dwordx4 v[162:165], v232, s[4:5] nt
	s_add_u32 s4, s72, 0x16000
	s_addc_u32 s5, s73, 0
	global_load_dwordx4 v[194:197], v232, s[4:5] nt
	s_waitcnt vmcnt(18)
	v_lshlrev_b32_e32 v224, 16, v166
	v_and_b32_e32 v225, 0xffff0000, v166
	v_lshlrev_b32_e32 v228, 16, v198
	v_and_b32_e32 v229, 0xffff0000, v198
	v_pk_fma_f32 v[94:95], v[94:95], v[224:225], v[228:229]
	v_lshlrev_b32_e32 v226, 16, v167
	v_and_b32_e32 v227, 0xffff0000, v167
	v_lshlrev_b32_e32 v230, 16, v199
	v_and_b32_e32 v231, 0xffff0000, v199
	v_pk_fma_f32 v[96:97], v[96:97], v[226:227], v[230:231]
	v_lshlrev_b32_e32 v224, 16, v168
	v_and_b32_e32 v225, 0xffff0000, v168
	v_lshlrev_b32_e32 v228, 16, v200
	v_and_b32_e32 v229, 0xffff0000, v200
	v_pk_fma_f32 v[90:91], v[90:91], v[224:225], v[228:229]
	v_lshlrev_b32_e32 v226, 16, v169
	v_and_b32_e32 v227, 0xffff0000, v169
	v_lshlrev_b32_e32 v230, 16, v201
	v_and_b32_e32 v231, 0xffff0000, v201
	v_pk_fma_f32 v[92:93], v[92:93], v[226:227], v[230:231]
	v_cvt_pk_bf16_f32 v94, v94, v95
	v_cvt_pk_bf16_f32 v95, v96, v97
	v_cvt_pk_bf16_f32 v96, v90, v91
	v_cvt_pk_bf16_f32 v97, v92, v93
	s_add_u32 s76, s74, 0x40000
	s_addc_u32 s77, s75, 0
	global_store_dwordx4 v233, v[94:97], s[76:77]
	s_add_u32 s4, s70, 0x18000
	s_addc_u32 s5, s71, 0
	global_load_dwordx4 v[166:169], v232, s[4:5] nt
	s_add_u32 s4, s72, 0x18000
	s_addc_u32 s5, s73, 0
	global_load_dwordx4 v[198:201], v232, s[4:5] nt
	s_waitcnt vmcnt(19)
	v_lshlrev_b32_e32 v224, 16, v170
	v_and_b32_e32 v225, 0xffff0000, v170
	v_lshlrev_b32_e32 v228, 16, v202
	v_and_b32_e32 v229, 0xffff0000, v202
	v_pk_fma_f32 v[86:87], v[86:87], v[224:225], v[228:229]
	v_lshlrev_b32_e32 v226, 16, v171
	v_and_b32_e32 v227, 0xffff0000, v171
	v_lshlrev_b32_e32 v230, 16, v203
	v_and_b32_e32 v231, 0xffff0000, v203
	v_pk_fma_f32 v[88:89], v[88:89], v[226:227], v[230:231]
	v_lshlrev_b32_e32 v224, 16, v172
	v_and_b32_e32 v225, 0xffff0000, v172
	v_lshlrev_b32_e32 v228, 16, v204
	v_and_b32_e32 v229, 0xffff0000, v204
	v_pk_fma_f32 v[82:83], v[82:83], v[224:225], v[228:229]
	v_lshlrev_b32_e32 v226, 16, v173
	v_and_b32_e32 v227, 0xffff0000, v173
	v_lshlrev_b32_e32 v230, 16, v205
	v_and_b32_e32 v231, 0xffff0000, v205
	v_pk_fma_f32 v[84:85], v[84:85], v[226:227], v[230:231]
	v_cvt_pk_bf16_f32 v86, v86, v87
	v_cvt_pk_bf16_f32 v87, v88, v89
	v_cvt_pk_bf16_f32 v88, v82, v83
	v_cvt_pk_bf16_f32 v89, v84, v85
	s_add_u32 s76, s74, 0x48000
	s_addc_u32 s77, s75, 0
	global_store_dwordx4 v233, v[86:89], s[76:77]
	s_add_u32 s4, s70, 0x1a000
	s_addc_u32 s5, s71, 0
	global_load_dwordx4 v[170:173], v232, s[4:5] nt
	s_add_u32 s4, s72, 0x1a000
	s_addc_u32 s5, s73, 0
	global_load_dwordx4 v[202:205], v232, s[4:5] nt
	s_waitcnt vmcnt(20)
	v_lshlrev_b32_e32 v224, 16, v174
	v_and_b32_e32 v225, 0xffff0000, v174
	v_lshlrev_b32_e32 v228, 16, v206
	v_and_b32_e32 v229, 0xffff0000, v206
	v_pk_fma_f32 v[78:79], v[78:79], v[224:225], v[228:229]
	v_lshlrev_b32_e32 v226, 16, v175
	v_and_b32_e32 v227, 0xffff0000, v175
	v_lshlrev_b32_e32 v230, 16, v207
	v_and_b32_e32 v231, 0xffff0000, v207
	v_pk_fma_f32 v[80:81], v[80:81], v[226:227], v[230:231]
	v_lshlrev_b32_e32 v224, 16, v176
	v_and_b32_e32 v225, 0xffff0000, v176
	v_lshlrev_b32_e32 v228, 16, v208
	v_and_b32_e32 v229, 0xffff0000, v208
	v_pk_fma_f32 v[74:75], v[74:75], v[224:225], v[228:229]
	v_lshlrev_b32_e32 v226, 16, v177
	v_and_b32_e32 v227, 0xffff0000, v177
	v_lshlrev_b32_e32 v230, 16, v209
	v_and_b32_e32 v231, 0xffff0000, v209
	v_pk_fma_f32 v[76:77], v[76:77], v[226:227], v[230:231]
	v_cvt_pk_bf16_f32 v78, v78, v79
	v_cvt_pk_bf16_f32 v79, v80, v81
	v_cvt_pk_bf16_f32 v80, v74, v75
	v_cvt_pk_bf16_f32 v81, v76, v77
	s_add_u32 s76, s74, 0x50000
	s_addc_u32 s77, s75, 0
	global_store_dwordx4 v233, v[78:81], s[76:77]
	s_add_u32 s4, s70, 0x1c000
	s_addc_u32 s5, s71, 0
	global_load_dwordx4 v[174:177], v232, s[4:5] nt
	s_add_u32 s4, s72, 0x1c000
	s_addc_u32 s5, s73, 0
	global_load_dwordx4 v[206:209], v232, s[4:5] nt
	s_waitcnt vmcnt(21)
	v_lshlrev_b32_e32 v224, 16, v178
	v_and_b32_e32 v225, 0xffff0000, v178
	v_lshlrev_b32_e32 v228, 16, v210
	v_and_b32_e32 v229, 0xffff0000, v210
	v_pk_fma_f32 v[70:71], v[70:71], v[224:225], v[228:229]
	v_lshlrev_b32_e32 v226, 16, v179
	v_and_b32_e32 v227, 0xffff0000, v179
	v_lshlrev_b32_e32 v230, 16, v211
	v_and_b32_e32 v231, 0xffff0000, v211
	v_pk_fma_f32 v[72:73], v[72:73], v[226:227], v[230:231]
	v_lshlrev_b32_e32 v224, 16, v180
	v_and_b32_e32 v225, 0xffff0000, v180
	v_lshlrev_b32_e32 v228, 16, v212
	v_and_b32_e32 v229, 0xffff0000, v212
	v_pk_fma_f32 v[66:67], v[66:67], v[224:225], v[228:229]
	v_lshlrev_b32_e32 v226, 16, v181
	v_and_b32_e32 v227, 0xffff0000, v181
	v_lshlrev_b32_e32 v230, 16, v213
	v_and_b32_e32 v231, 0xffff0000, v213
	v_pk_fma_f32 v[68:69], v[68:69], v[226:227], v[230:231]
	v_cvt_pk_bf16_f32 v70, v70, v71
	v_cvt_pk_bf16_f32 v71, v72, v73
	v_cvt_pk_bf16_f32 v72, v66, v67
	v_cvt_pk_bf16_f32 v73, v68, v69
	s_add_u32 s76, s74, 0x58000
	s_addc_u32 s77, s75, 0
	global_store_dwordx4 v233, v[70:73], s[76:77]
	s_add_u32 s4, s70, 0x1e000
	s_addc_u32 s5, s71, 0
	global_load_dwordx4 v[178:181], v232, s[4:5] nt
	s_add_u32 s4, s72, 0x1e000
	s_addc_u32 s5, s73, 0
	global_load_dwordx4 v[210:213], v232, s[4:5] nt
	s_waitcnt vmcnt(21)
	v_lshlrev_b32_e32 v224, 16, v130
	v_and_b32_e32 v225, 0xffff0000, v130
	v_lshlrev_b32_e32 v228, 16, v182
	v_and_b32_e32 v229, 0xffff0000, v182
	v_pk_fma_f32 v[62:63], v[62:63], v[224:225], v[228:229]
	v_lshlrev_b32_e32 v226, 16, v131
	v_and_b32_e32 v227, 0xffff0000, v131
	v_lshlrev_b32_e32 v230, 16, v183
	v_and_b32_e32 v231, 0xffff0000, v183
	v_pk_fma_f32 v[64:65], v[64:65], v[226:227], v[230:231]
	v_lshlrev_b32_e32 v224, 16, v132
	v_and_b32_e32 v225, 0xffff0000, v132
	v_lshlrev_b32_e32 v228, 16, v184
	v_and_b32_e32 v229, 0xffff0000, v184
	v_pk_fma_f32 v[58:59], v[58:59], v[224:225], v[228:229]
	v_lshlrev_b32_e32 v226, 16, v133
	v_and_b32_e32 v227, 0xffff0000, v133
	v_lshlrev_b32_e32 v230, 16, v185
	v_and_b32_e32 v231, 0xffff0000, v185
	v_pk_fma_f32 v[60:61], v[60:61], v[226:227], v[230:231]
	v_cvt_pk_bf16_f32 v62, v62, v63
	v_cvt_pk_bf16_f32 v63, v64, v65
	v_cvt_pk_bf16_f32 v64, v58, v59
	v_cvt_pk_bf16_f32 v65, v60, v61
	s_add_u32 s76, s74, 0x100
	s_addc_u32 s77, s75, 0
	global_store_dwordx4 v233, v[62:65], s[76:77]
	s_waitcnt vmcnt(19)
	v_lshlrev_b32_e32 v224, 16, v134
	v_and_b32_e32 v225, 0xffff0000, v134
	v_lshlrev_b32_e32 v228, 16, v186
	v_and_b32_e32 v229, 0xffff0000, v186
	v_pk_fma_f32 v[54:55], v[54:55], v[224:225], v[228:229]
	v_lshlrev_b32_e32 v226, 16, v135
	v_and_b32_e32 v227, 0xffff0000, v135
	v_lshlrev_b32_e32 v230, 16, v187
	v_and_b32_e32 v231, 0xffff0000, v187
	v_pk_fma_f32 v[56:57], v[56:57], v[226:227], v[230:231]
	v_lshlrev_b32_e32 v224, 16, v136
	v_and_b32_e32 v225, 0xffff0000, v136
	v_lshlrev_b32_e32 v228, 16, v188
	v_and_b32_e32 v229, 0xffff0000, v188
	v_pk_fma_f32 v[50:51], v[50:51], v[224:225], v[228:229]
	v_lshlrev_b32_e32 v226, 16, v137
	v_and_b32_e32 v227, 0xffff0000, v137
	v_lshlrev_b32_e32 v230, 16, v189
	v_and_b32_e32 v231, 0xffff0000, v189
	v_pk_fma_f32 v[52:53], v[52:53], v[226:227], v[230:231]
	v_cvt_pk_bf16_f32 v54, v54, v55
	v_cvt_pk_bf16_f32 v55, v56, v57
	v_cvt_pk_bf16_f32 v56, v50, v51
	v_cvt_pk_bf16_f32 v57, v52, v53
	s_add_u32 s76, s74, 0x8100
	s_addc_u32 s77, s75, 0
	global_store_dwordx4 v233, v[54:57], s[76:77]
	s_waitcnt vmcnt(17)
	v_lshlrev_b32_e32 v224, 16, v156
	v_and_b32_e32 v225, 0xffff0000, v156
	v_lshlrev_b32_e32 v228, 16, v190
	v_and_b32_e32 v229, 0xffff0000, v190
	v_pk_fma_f32 v[46:47], v[46:47], v[224:225], v[228:229]
	v_lshlrev_b32_e32 v226, 16, v157
	v_and_b32_e32 v227, 0xffff0000, v157
	v_lshlrev_b32_e32 v230, 16, v191
	v_and_b32_e32 v231, 0xffff0000, v191
	v_pk_fma_f32 v[48:49], v[48:49], v[226:227], v[230:231]
	v_lshlrev_b32_e32 v224, 16, v158
	v_and_b32_e32 v225, 0xffff0000, v158
	v_lshlrev_b32_e32 v228, 16, v192
	v_and_b32_e32 v229, 0xffff0000, v192
	v_pk_fma_f32 v[42:43], v[42:43], v[224:225], v[228:229]
	v_lshlrev_b32_e32 v226, 16, v159
	v_and_b32_e32 v227, 0xffff0000, v159
	v_lshlrev_b32_e32 v230, 16, v193
	v_and_b32_e32 v231, 0xffff0000, v193
	v_pk_fma_f32 v[44:45], v[44:45], v[226:227], v[230:231]
	v_cvt_pk_bf16_f32 v46, v46, v47
	v_cvt_pk_bf16_f32 v47, v48, v49
	v_cvt_pk_bf16_f32 v48, v42, v43
	v_cvt_pk_bf16_f32 v49, v44, v45
	s_add_u32 s76, s74, 0x10100
	s_addc_u32 s77, s75, 0
	global_store_dwordx4 v233, v[46:49], s[76:77]
	s_waitcnt vmcnt(15)
	v_lshlrev_b32_e32 v224, 16, v162
	v_and_b32_e32 v225, 0xffff0000, v162
	v_lshlrev_b32_e32 v228, 16, v194
	v_and_b32_e32 v229, 0xffff0000, v194
	v_pk_fma_f32 v[38:39], v[38:39], v[224:225], v[228:229]
	v_lshlrev_b32_e32 v226, 16, v163
	v_and_b32_e32 v227, 0xffff0000, v163
	v_lshlrev_b32_e32 v230, 16, v195
	v_and_b32_e32 v231, 0xffff0000, v195
	v_pk_fma_f32 v[40:41], v[40:41], v[226:227], v[230:231]
	v_lshlrev_b32_e32 v224, 16, v164
	v_and_b32_e32 v225, 0xffff0000, v164
	v_lshlrev_b32_e32 v228, 16, v196
	v_and_b32_e32 v229, 0xffff0000, v196
	v_pk_fma_f32 v[34:35], v[34:35], v[224:225], v[228:229]
	v_lshlrev_b32_e32 v226, 16, v165
	v_and_b32_e32 v227, 0xffff0000, v165
	v_lshlrev_b32_e32 v230, 16, v197
	v_and_b32_e32 v231, 0xffff0000, v197
	v_pk_fma_f32 v[36:37], v[36:37], v[226:227], v[230:231]
	v_cvt_pk_bf16_f32 v38, v38, v39
	v_cvt_pk_bf16_f32 v39, v40, v41
	v_cvt_pk_bf16_f32 v40, v34, v35
	v_cvt_pk_bf16_f32 v41, v36, v37
	s_add_u32 s76, s74, 0x18100
	s_addc_u32 s77, s75, 0
	global_store_dwordx4 v233, v[38:41], s[76:77]
	s_waitcnt vmcnt(13)
	v_lshlrev_b32_e32 v224, 16, v166
	v_and_b32_e32 v225, 0xffff0000, v166
	v_lshlrev_b32_e32 v228, 16, v198
	v_and_b32_e32 v229, 0xffff0000, v198
	v_pk_fma_f32 v[30:31], v[30:31], v[224:225], v[228:229]
	v_lshlrev_b32_e32 v226, 16, v167
	v_and_b32_e32 v227, 0xffff0000, v167
	v_lshlrev_b32_e32 v230, 16, v199
	v_and_b32_e32 v231, 0xffff0000, v199
	v_pk_fma_f32 v[32:33], v[32:33], v[226:227], v[230:231]
	v_lshlrev_b32_e32 v224, 16, v168
	v_and_b32_e32 v225, 0xffff0000, v168
	v_lshlrev_b32_e32 v228, 16, v200
	v_and_b32_e32 v229, 0xffff0000, v200
	v_pk_fma_f32 v[26:27], v[26:27], v[224:225], v[228:229]
	v_lshlrev_b32_e32 v226, 16, v169
	v_and_b32_e32 v227, 0xffff0000, v169
	v_lshlrev_b32_e32 v230, 16, v201
	v_and_b32_e32 v231, 0xffff0000, v201
	v_pk_fma_f32 v[28:29], v[28:29], v[226:227], v[230:231]
	v_cvt_pk_bf16_f32 v30, v30, v31
	v_cvt_pk_bf16_f32 v31, v32, v33
	v_cvt_pk_bf16_f32 v32, v26, v27
	v_cvt_pk_bf16_f32 v33, v28, v29
	s_add_u32 s76, s74, 0x40100
	s_addc_u32 s77, s75, 0
	global_store_dwordx4 v233, v[30:33], s[76:77]
	s_waitcnt vmcnt(11)
	v_lshlrev_b32_e32 v224, 16, v170
	v_and_b32_e32 v225, 0xffff0000, v170
	v_lshlrev_b32_e32 v228, 16, v202
	v_and_b32_e32 v229, 0xffff0000, v202
	v_pk_fma_f32 v[22:23], v[22:23], v[224:225], v[228:229]
	v_lshlrev_b32_e32 v226, 16, v171
	v_and_b32_e32 v227, 0xffff0000, v171
	v_lshlrev_b32_e32 v230, 16, v203
	v_and_b32_e32 v231, 0xffff0000, v203
	v_pk_fma_f32 v[24:25], v[24:25], v[226:227], v[230:231]
	v_lshlrev_b32_e32 v224, 16, v172
	v_and_b32_e32 v225, 0xffff0000, v172
	v_lshlrev_b32_e32 v228, 16, v204
	v_and_b32_e32 v229, 0xffff0000, v204
	v_pk_fma_f32 v[18:19], v[18:19], v[224:225], v[228:229]
	v_lshlrev_b32_e32 v226, 16, v173
	v_and_b32_e32 v227, 0xffff0000, v173
	v_lshlrev_b32_e32 v230, 16, v205
	v_and_b32_e32 v231, 0xffff0000, v205
	v_pk_fma_f32 v[20:21], v[20:21], v[226:227], v[230:231]
	v_cvt_pk_bf16_f32 v22, v22, v23
	v_cvt_pk_bf16_f32 v23, v24, v25
	v_cvt_pk_bf16_f32 v24, v18, v19
	v_cvt_pk_bf16_f32 v25, v20, v21
	s_add_u32 s76, s74, 0x48100
	s_addc_u32 s77, s75, 0
	global_store_dwordx4 v233, v[22:25], s[76:77]
	s_waitcnt vmcnt(9)
	v_lshlrev_b32_e32 v224, 16, v174
	v_and_b32_e32 v225, 0xffff0000, v174
	v_lshlrev_b32_e32 v228, 16, v206
	v_and_b32_e32 v229, 0xffff0000, v206
	v_pk_fma_f32 v[14:15], v[14:15], v[224:225], v[228:229]
	v_lshlrev_b32_e32 v226, 16, v175
	v_and_b32_e32 v227, 0xffff0000, v175
	v_lshlrev_b32_e32 v230, 16, v207
	v_and_b32_e32 v231, 0xffff0000, v207
	v_pk_fma_f32 v[16:17], v[16:17], v[226:227], v[230:231]
	v_lshlrev_b32_e32 v224, 16, v176
	v_and_b32_e32 v225, 0xffff0000, v176
	v_lshlrev_b32_e32 v228, 16, v208
	v_and_b32_e32 v229, 0xffff0000, v208
	v_pk_fma_f32 v[10:11], v[10:11], v[224:225], v[228:229]
	v_lshlrev_b32_e32 v226, 16, v177
	v_and_b32_e32 v227, 0xffff0000, v177
	v_lshlrev_b32_e32 v230, 16, v209
	v_and_b32_e32 v231, 0xffff0000, v209
	v_pk_fma_f32 v[12:13], v[12:13], v[226:227], v[230:231]
	v_cvt_pk_bf16_f32 v14, v14, v15
	v_cvt_pk_bf16_f32 v15, v16, v17
	v_cvt_pk_bf16_f32 v16, v10, v11
	v_cvt_pk_bf16_f32 v17, v12, v13
	s_add_u32 s76, s74, 0x50100
	s_addc_u32 s77, s75, 0
	global_store_dwordx4 v233, v[14:17], s[76:77]
	s_waitcnt vmcnt(7)
	v_lshlrev_b32_e32 v224, 16, v178
	v_and_b32_e32 v225, 0xffff0000, v178
	v_lshlrev_b32_e32 v228, 16, v210
	v_and_b32_e32 v229, 0xffff0000, v210
	v_pk_fma_f32 v[6:7], v[6:7], v[224:225], v[228:229]
	v_lshlrev_b32_e32 v226, 16, v179
	v_and_b32_e32 v227, 0xffff0000, v179
	v_lshlrev_b32_e32 v230, 16, v211
	v_and_b32_e32 v231, 0xffff0000, v211
	v_pk_fma_f32 v[8:9], v[8:9], v[226:227], v[230:231]
	v_lshlrev_b32_e32 v224, 16, v180
	v_and_b32_e32 v225, 0xffff0000, v180
	v_lshlrev_b32_e32 v228, 16, v212
	v_and_b32_e32 v229, 0xffff0000, v212
	v_pk_fma_f32 v[0:1], v[0:1], v[224:225], v[228:229]
	v_lshlrev_b32_e32 v226, 16, v181
	v_and_b32_e32 v227, 0xffff0000, v181
	v_lshlrev_b32_e32 v230, 16, v213
	v_and_b32_e32 v231, 0xffff0000, v213
	v_pk_fma_f32 v[2:3], v[2:3], v[226:227], v[230:231]
	v_cvt_pk_bf16_f32 v6, v6, v7
	v_cvt_pk_bf16_f32 v7, v8, v9
	v_cvt_pk_bf16_f32 v8, v0, v1
	v_cvt_pk_bf16_f32 v9, v2, v3
	s_add_u32 s76, s74, 0x58100
	s_addc_u32 s77, s75, 0
	global_store_dwordx4 v233, v[6:9], s[76:77]
